# mixer items and queue loops: redundant barriers removed (item-top barrier duplicates the queue loop's id-broadcast barrier; loop-head barrier duplicates the items' own)
# baseline (speedup 1.0000x reference)
.LBB0_548:
	s_or_b64 exec, exec, s[0:1]
	s_waitcnt lgkmcnt(0)
	s_barrier
	ds_read_b32 v0, v3 offset:16
	s_movk_i32 s0, 0x10ff
	s_waitcnt lgkmcnt(0)
	v_cmp_lt_i32_e32 vcc, s0, v0
	v_readfirstlane_b32 s6, v0
	s_mov_b64 s[0:1], -1
	s_cbranch_vccnz .LBB0_543
	s_cmpk_gt_i32 s6, 0x43f
	s_cbranch_scc0 .LBB0_760
	s_cmpk_gt_u32 s6, 0x65f
	s_cbranch_scc0 .LBB0_719
	s_cmpk_gt_u32 s6, 0x87f
	s_cbranch_scc0 .LBB0_561
	s_add_i32 s0, s6, 0xf780
	s_and_b32 s1, s0, 0xffff
	s_mul_i32 s5, s1, 0xf0f1
	s_lshr_b32 s7, s5, 22
	s_mulk_i32 s7, 0x44
	s_sub_i32 s0, s0, s7
	s_lshr_b32 s4, s5, 24
	s_and_b32 s7, s0, 0xffff
	s_mul_i32 s1, s4, 0xee0000
	s_mul_i32 s0, s7, 0x38000
	s_add_i32 s22, s1, s0
	v_mov_b32_e32 v0, v222
	s_lshl_b64 s[0:1], s[22:23], 1
	s_add_u32 s0, s24, s0
	s_addc_u32 s1, s25, s1
	s_bfe_u32 s5, s5, 0x20016
	v_mov_b32_e32 v0, v222
	s_lshl_b32 s10, s5, 6
	v_and_b32_e32 v6, 63, v0
	v_ashrrev_i32_e32 v4, 6, v0
	v_or_b32_e32 v1, s10, v6
	v_lshlrev_b32_e32 v24, 4, v4
	v_lshlrev_b32_e32 v2, 1, v1
	v_lshl_add_u64 v[8:9], s[0:1], 0, v[2:3]
	v_or_b32_e32 v2, 2, v24
	v_or_b32_e32 v1, 1, v24
	v_mad_i64_i32 v[14:15], s[12:13], v2, s48, v[8:9]
	v_or_b32_e32 v2, 3, v24
	v_mad_i64_i32 v[10:11], s[12:13], v24, s48, v[8:9]
	v_mad_i64_i32 v[12:13], s[12:13], v1, s48, v[8:9]
	v_mad_i64_i32 v[16:17], s[12:13], v2, s48, v[8:9]
	v_mad_i64_i32 v[128:129], s[12:13], v24, s48, v[8:9]
	global_load_ushort v96, v[128:129], off offset:1024
	global_load_ushort v80, v[128:129], off offset:2560
	v_or_b32_e32 v137, 1, v24
	v_mad_i64_i32 v[130:131], s[12:13], v137, s48, v[8:9]
	global_load_ushort v97, v[130:131], off offset:1024
	global_load_ushort v81, v[130:131], off offset:2560
	v_or_b32_e32 v138, 2, v24
	v_mad_i64_i32 v[132:133], s[12:13], v138, s48, v[8:9]
	global_load_ushort v98, v[132:133], off offset:1024
	global_load_ushort v82, v[132:133], off offset:2560
	v_or_b32_e32 v139, 3, v24
	v_mad_i64_i32 v[134:135], s[12:13], v139, s48, v[8:9]
	global_load_ushort v99, v[134:135], off offset:1024
	global_load_ushort v83, v[134:135], off offset:2560
	v_or_b32_e32 v136, 4, v24
	v_mad_i64_i32 v[128:129], s[12:13], v136, s48, v[8:9]
	global_load_ushort v100, v[128:129], off offset:1024
	global_load_ushort v84, v[128:129], off offset:2560
	v_or_b32_e32 v137, 5, v24
	v_mad_i64_i32 v[130:131], s[12:13], v137, s48, v[8:9]
	global_load_ushort v101, v[130:131], off offset:1024
	global_load_ushort v85, v[130:131], off offset:2560
	v_or_b32_e32 v138, 6, v24
	v_mad_i64_i32 v[132:133], s[12:13], v138, s48, v[8:9]
	global_load_ushort v102, v[132:133], off offset:1024
	global_load_ushort v86, v[132:133], off offset:2560
	v_or_b32_e32 v139, 7, v24
	v_mad_i64_i32 v[134:135], s[12:13], v139, s48, v[8:9]
	global_load_ushort v103, v[134:135], off offset:1024
	global_load_ushort v87, v[134:135], off offset:2560
	v_or_b32_e32 v136, 8, v24
	v_mad_i64_i32 v[128:129], s[12:13], v136, s48, v[8:9]
	global_load_ushort v104, v[128:129], off offset:1024
	global_load_ushort v88, v[128:129], off offset:2560
	v_or_b32_e32 v137, 9, v24
	v_mad_i64_i32 v[130:131], s[12:13], v137, s48, v[8:9]
	global_load_ushort v105, v[130:131], off offset:1024
	global_load_ushort v89, v[130:131], off offset:2560
	v_or_b32_e32 v138, 10, v24
	v_mad_i64_i32 v[132:133], s[12:13], v138, s48, v[8:9]
	global_load_ushort v106, v[132:133], off offset:1024
	global_load_ushort v90, v[132:133], off offset:2560
	v_or_b32_e32 v139, 11, v24
	v_mad_i64_i32 v[134:135], s[12:13], v139, s48, v[8:9]
	global_load_ushort v107, v[134:135], off offset:1024
	global_load_ushort v91, v[134:135], off offset:2560
	v_or_b32_e32 v136, 12, v24
	v_mad_i64_i32 v[128:129], s[12:13], v136, s48, v[8:9]
	global_load_ushort v108, v[128:129], off offset:1024
	global_load_ushort v92, v[128:129], off offset:2560
	v_or_b32_e32 v137, 13, v24
	v_mad_i64_i32 v[130:131], s[12:13], v137, s48, v[8:9]
	global_load_ushort v109, v[130:131], off offset:1024
	global_load_ushort v93, v[130:131], off offset:2560
	v_or_b32_e32 v138, 14, v24
	v_mad_i64_i32 v[132:133], s[12:13], v138, s48, v[8:9]
	global_load_ushort v110, v[132:133], off offset:1024
	global_load_ushort v94, v[132:133], off offset:2560
	v_or_b32_e32 v139, 15, v24
	v_mad_i64_i32 v[134:135], s[12:13], v139, s48, v[8:9]
	global_load_ushort v111, v[134:135], off offset:1024
	global_load_ushort v95, v[134:135], off offset:2560
	v_lshrrev_b32_e32 v180, 3, v222
	v_mul_u32_u24_e32 v180, 0x1c00, v180
	v_lshlrev_b32_e32 v181, 4, v222
	v_and_b32_e32 v181, 0x70, v181
	s_lshl_b32 s99, s5, 7
	v_add3_u32 v180, v180, v181, s99
	global_load_dwordx4 v[140:143], v180, s[0:1] offset:1536
	v_add_u32_e32 v181, 0x38000, v180
	global_load_dwordx4 v[144:147], v181, s[0:1] offset:1536
	global_load_ushort v2, v[10:11], off offset:2048
	global_load_ushort v5, v[12:13], off offset:2048
	global_load_ushort v7, v[14:15], off offset:2048
	global_load_ushort v18, v[16:17], off offset:2048
	global_load_ushort v19, v[16:17], off offset:1024
	global_load_ushort v20, v[14:15], off offset:1024
	global_load_ushort v21, v[12:13], off offset:1024
	global_load_ushort v22, v[10:11], off offset:1024
	v_or_b32_e32 v10, 4, v24
	v_or_b32_e32 v12, 5, v24
	v_or_b32_e32 v14, 6, v24
	v_or_b32_e32 v16, 7, v24
	v_mad_i64_i32 v[10:11], s[12:13], v10, s48, v[8:9]
	v_mad_i64_i32 v[12:13], s[12:13], v12, s48, v[8:9]
	v_mad_i64_i32 v[14:15], s[12:13], v14, s48, v[8:9]
	v_mad_i64_i32 v[16:17], s[12:13], v16, s48, v[8:9]
	global_load_ushort v23, v[10:11], off offset:2048
	global_load_ushort v25, v[12:13], off offset:2048
	global_load_ushort v26, v[14:15], off offset:2048
	global_load_ushort v27, v[16:17], off offset:2048
	global_load_ushort v28, v[16:17], off offset:1024
	global_load_ushort v29, v[14:15], off offset:1024
	global_load_ushort v30, v[12:13], off offset:1024
	global_load_ushort v31, v[10:11], off offset:1024
	v_or_b32_e32 v10, 8, v24
	v_or_b32_e32 v12, 9, v24
	v_or_b32_e32 v14, 10, v24
	v_or_b32_e32 v16, 11, v24
	v_mad_i64_i32 v[10:11], s[12:13], v10, s48, v[8:9]
	v_mad_i64_i32 v[12:13], s[12:13], v12, s48, v[8:9]
	v_mad_i64_i32 v[14:15], s[12:13], v14, s48, v[8:9]
	v_mad_i64_i32 v[16:17], s[12:13], v16, s48, v[8:9]
	global_load_ushort v32, v[10:11], off offset:2048
	global_load_ushort v33, v[12:13], off offset:2048
	global_load_ushort v34, v[14:15], off offset:2048
	global_load_ushort v35, v[16:17], off offset:2048
	s_nop 0
	global_load_ushort v16, v[16:17], off offset:1024
	s_nop 0
	global_load_ushort v17, v[14:15], off offset:1024
	global_load_ushort v36, v[12:13], off offset:1024
	global_load_ushort v37, v[10:11], off offset:1024
	v_or_b32_e32 v10, 12, v24
	v_or_b32_e32 v12, 13, v24
	v_or_b32_e32 v14, 14, v24
	v_or_b32_e32 v38, 15, v24
	v_mad_i64_i32 v[10:11], s[12:13], v10, s48, v[8:9]
	v_mad_i64_i32 v[12:13], s[12:13], v12, s48, v[8:9]
	v_mad_i64_i32 v[14:15], s[12:13], v14, s48, v[8:9]
	v_mad_i64_i32 v[8:9], s[12:13], v38, s48, v[8:9]
	global_load_ushort v38, v[10:11], off offset:2048
	global_load_ushort v39, v[12:13], off offset:1024
	global_load_ushort v40, v[8:9], off offset:2048
	global_load_ushort v41, v[14:15], off offset:2048
	s_nop 0
	global_load_ushort v12, v[12:13], off offset:2048
	s_nop 0
	global_load_ushort v10, v[10:11], off offset:1024
	s_nop 0
	global_load_ushort v11, v[14:15], off offset:1024
	s_nop 0
	global_load_ushort v8, v[8:9], off offset:1024
	s_movk_i32 s8, 0x500
	s_waitcnt vmcnt(43)
	v_mul_lo_u32 v55, v4, s8
	v_or_b32_e32 v55, v55, v6
	s_movk_i32 s8, 0x50
	s_lshl_b32 s22, s5, 7
	s_lshl_b32 s4, s4, 3
	s_lshl_b32 s5, s5, 1
	s_or_b32 s11, s5, s4
	v_cmp_lt_i32_e32 vcc, 63, v0
	s_waitcnt vmcnt(31)
	v_lshlrev_b32_e32 v2, 16, v2
	s_waitcnt vmcnt(30)
	v_lshlrev_b32_e32 v5, 16, v5
	s_waitcnt vmcnt(29)
	v_lshlrev_b32_e32 v14, 16, v7
	v_add_f32_e32 v7, 0, v2
	s_waitcnt vmcnt(28)
	v_lshlrev_b32_e32 v18, 16, v18
	s_waitcnt vmcnt(26)
	v_lshlrev_b32_e32 v15, 16, v20
	s_waitcnt vmcnt(25)
	v_lshlrev_b32_e32 v13, 16, v21
	s_waitcnt vmcnt(24)
	v_lshlrev_b32_e32 v9, 16, v22
	v_mul_f32_e32 v2, 0x3fb8aa3b, v2
	v_mul_f32_e32 v54, 0x3fb8aa3b, v7
	v_exp_f32_e32 v2, v2
	v_exp_f32_e32 v54, v54
	v_lshlrev_b32_e32 v19, 16, v19
	s_waitcnt vmcnt(23)
	v_lshlrev_b32_e32 v20, 16, v23
	s_waitcnt vmcnt(22)
	v_lshlrev_b32_e32 v22, 16, v25
	s_waitcnt vmcnt(21)
	v_lshlrev_b32_e32 v25, 16, v26
	s_waitcnt vmcnt(20)
	v_lshlrev_b32_e32 v27, 16, v27
	v_sub_f32_e32 v2, 1.0, v2
	s_waitcnt vmcnt(18)
	v_lshlrev_b32_e32 v26, 16, v29
	s_waitcnt vmcnt(17)
	v_lshlrev_b32_e32 v23, 16, v30
	s_waitcnt vmcnt(16)
	v_lshlrev_b32_e32 v21, 16, v31
	v_mul_f32_e32 v9, v54, v9
	v_lshl_add_u32 v54, v55, 1, 32
	v_cvt_pk_bf16_f32 v9, v9, s0
	ds_write_b16 v54, v9
	v_lshlrev_b32_e32 v28, 16, v28
	s_waitcnt vmcnt(15)
	v_lshlrev_b32_e32 v29, 16, v32
	s_waitcnt vmcnt(14)
	v_lshlrev_b32_e32 v31, 16, v33
	s_waitcnt vmcnt(13)
	v_lshlrev_b32_e32 v33, 16, v34
	s_waitcnt vmcnt(12)
	v_lshlrev_b32_e32 v34, 16, v35
	s_waitcnt vmcnt(11)
	v_lshlrev_b32_e32 v16, 16, v16
	s_waitcnt vmcnt(10)
	v_lshlrev_b32_e32 v17, 16, v17
	s_waitcnt vmcnt(9)
	v_lshlrev_b32_e32 v32, 16, v36
	s_waitcnt vmcnt(8)
	v_lshlrev_b32_e32 v30, 16, v37
	s_waitcnt vmcnt(7)
	v_lshlrev_b32_e32 v35, 16, v38
	s_waitcnt vmcnt(6)
	v_lshlrev_b32_e32 v38, 16, v39
	s_waitcnt vmcnt(5)
	v_lshlrev_b32_e32 v40, 16, v40
	s_waitcnt vmcnt(4)
	v_lshlrev_b32_e32 v39, 16, v41
	s_waitcnt vmcnt(3)
	v_lshlrev_b32_e32 v37, 16, v12
	s_waitcnt vmcnt(2)
	v_lshlrev_b32_e32 v36, 16, v10
	s_waitcnt vmcnt(1)
	v_lshlrev_b32_e32 v41, 16, v11
	s_waitcnt vmcnt(0)
	v_lshlrev_b32_e32 v42, 16, v8
	v_add_f32_e32 v8, v7, v5
	v_add_f32_e32 v10, v8, v14
	v_add_f32_e32 v11, v10, v18
	v_add_f32_e32 v12, v11, v20
	v_add_f32_e32 v43, v12, v22
	v_add_f32_e32 v44, v43, v25
	v_add_f32_e32 v45, v44, v27
	v_add_f32_e32 v46, v45, v29
	v_add_f32_e32 v47, v46, v31
	v_add_f32_e32 v48, v47, v33
	v_add_f32_e32 v49, v48, v34
	v_add_f32_e32 v50, v49, v35
	v_add_f32_e32 v51, v50, v37
	v_add_f32_e32 v52, v51, v39
	v_add_f32_e32 v53, v52, v40
	v_sub_f32_e32 v7, v53, v7
	v_mul_f32_e32 v7, 0x3fb8aa3b, v7
	v_exp_f32_e32 v7, v7
	v_mul_f32_e32 v5, 0x3fb8aa3b, v5
	v_exp_f32_e32 v5, v5
	v_mul_f32_e32 v2, v2, v7
	v_cvt_pk_bf16_f32 v2, v2, s0
	ds_write_b16 v54, v2 offset:20480
	v_mul_f32_e32 v2, 0x3fb8aa3b, v8
	v_exp_f32_e32 v2, v2
	v_mad_u64_u32 v[6:7], s[12:13], v1, s8, v[6:7]
	v_sub_f32_e32 v5, 1.0, v5
	v_mul_f32_e32 v1, v2, v13
	v_sub_f32_e32 v2, v53, v8
	v_mul_f32_e32 v2, 0x3fb8aa3b, v2
	v_exp_f32_e32 v2, v2
	v_cvt_pk_bf16_f32 v1, v1, s0
	v_lshl_add_u32 v54, v6, 1, 32
	ds_write_b16 v54, v1
	v_mul_f32_e32 v1, v5, v2
	v_mul_f32_e32 v2, 0x3fb8aa3b, v14
	v_mul_f32_e32 v5, 0x3fb8aa3b, v10
	v_exp_f32_e32 v2, v2
	v_exp_f32_e32 v5, v5
	v_cvt_pk_bf16_f32 v1, v1, s0
	ds_write_b16 v54, v1 offset:20480
	v_sub_f32_e32 v1, 1.0, v2
	v_mul_f32_e32 v2, v5, v15
	v_sub_f32_e32 v5, v53, v10
	v_mul_f32_e32 v5, 0x3fb8aa3b, v5
	v_cvt_pk_bf16_f32 v2, v2, s0
	v_exp_f32_e32 v5, v5
	ds_write_b16 v54, v2 offset:160
	v_mul_f32_e32 v2, 0x3fb8aa3b, v18
	v_exp_f32_e32 v2, v2
	v_mul_f32_e32 v1, v1, v5
	v_cvt_pk_bf16_f32 v1, v1, s0
	ds_write_b16 v54, v1 offset:20640
	v_sub_f32_e32 v1, 1.0, v2
	v_mul_f32_e32 v2, 0x3fb8aa3b, v11
	v_exp_f32_e32 v2, v2
	v_sub_f32_e32 v5, v53, v11
	v_mul_f32_e32 v5, 0x3fb8aa3b, v5
	v_exp_f32_e32 v5, v5
	v_mul_f32_e32 v2, v2, v19
	v_cvt_pk_bf16_f32 v2, v2, s0
	ds_write_b16 v54, v2 offset:320
	v_mul_f32_e32 v1, v1, v5
	v_mul_f32_e32 v2, 0x3fb8aa3b, v20
	v_mul_f32_e32 v5, 0x3fb8aa3b, v12
	v_exp_f32_e32 v2, v2
	v_exp_f32_e32 v5, v5
	v_cvt_pk_bf16_f32 v1, v1, s0
	ds_write_b16 v54, v1 offset:20800
	v_sub_f32_e32 v1, 1.0, v2
	v_mul_f32_e32 v2, v5, v21
	v_sub_f32_e32 v5, v53, v12
	v_mul_f32_e32 v5, 0x3fb8aa3b, v5
	v_cvt_pk_bf16_f32 v2, v2, s0
	v_exp_f32_e32 v5, v5
	ds_write_b16 v54, v2 offset:480
	v_mul_f32_e32 v2, 0x3fb8aa3b, v22
	v_exp_f32_e32 v2, v2
	v_mul_f32_e32 v1, v1, v5
	v_cvt_pk_bf16_f32 v1, v1, s0
	ds_write_b16 v54, v1 offset:20960
	v_sub_f32_e32 v1, 1.0, v2
	v_mul_f32_e32 v2, 0x3fb8aa3b, v43
	v_exp_f32_e32 v2, v2
	v_sub_f32_e32 v5, v53, v43
	v_mul_f32_e32 v5, 0x3fb8aa3b, v5
	v_exp_f32_e32 v5, v5
	v_mul_f32_e32 v2, v2, v23
	v_cvt_pk_bf16_f32 v2, v2, s0
	ds_write_b16 v54, v2 offset:640
	v_mul_f32_e32 v1, v1, v5
	v_mul_f32_e32 v2, 0x3fb8aa3b, v25
	v_mul_f32_e32 v5, 0x3fb8aa3b, v44
	v_exp_f32_e32 v2, v2
	v_exp_f32_e32 v5, v5
	v_cvt_pk_bf16_f32 v1, v1, s0
	ds_write_b16 v54, v1 offset:21120
	v_sub_f32_e32 v1, 1.0, v2
	v_mul_f32_e32 v2, v5, v26
	v_sub_f32_e32 v5, v53, v44
	v_mul_f32_e32 v5, 0x3fb8aa3b, v5
	v_cvt_pk_bf16_f32 v2, v2, s0
	v_exp_f32_e32 v5, v5
	ds_write_b16 v54, v2 offset:800
	v_mul_f32_e32 v2, 0x3fb8aa3b, v27
	v_exp_f32_e32 v2, v2
	v_mul_f32_e32 v1, v1, v5
	v_cvt_pk_bf16_f32 v1, v1, s0
	ds_write_b16 v54, v1 offset:21280
	v_sub_f32_e32 v1, 1.0, v2
	v_mul_f32_e32 v2, 0x3fb8aa3b, v45
	v_exp_f32_e32 v2, v2
	v_sub_f32_e32 v5, v53, v45
	v_mul_f32_e32 v5, 0x3fb8aa3b, v5
	v_exp_f32_e32 v5, v5
	v_mul_f32_e32 v2, v2, v28
	v_cvt_pk_bf16_f32 v2, v2, s0
	ds_write_b16 v54, v2 offset:960
	v_mul_f32_e32 v1, v1, v5
	v_mul_f32_e32 v2, 0x3fb8aa3b, v29
	v_mul_f32_e32 v5, 0x3fb8aa3b, v46
	v_exp_f32_e32 v2, v2
	v_exp_f32_e32 v5, v5
	v_cvt_pk_bf16_f32 v1, v1, s0
	ds_write_b16 v54, v1 offset:21440
	v_sub_f32_e32 v1, 1.0, v2
	v_mul_f32_e32 v2, v5, v30
	v_sub_f32_e32 v5, v53, v46
	v_mul_f32_e32 v5, 0x3fb8aa3b, v5
	v_cvt_pk_bf16_f32 v2, v2, s0
	v_exp_f32_e32 v5, v5
	ds_write_b16 v54, v2 offset:1120
	v_mul_f32_e32 v2, 0x3fb8aa3b, v31
	v_exp_f32_e32 v2, v2
	v_mul_f32_e32 v1, v1, v5
	v_cvt_pk_bf16_f32 v1, v1, s0
	ds_write_b16 v54, v1 offset:21600
	v_sub_f32_e32 v1, 1.0, v2
	v_mul_f32_e32 v2, 0x3fb8aa3b, v47
	v_exp_f32_e32 v2, v2
	v_sub_f32_e32 v5, v53, v47
	v_mul_f32_e32 v5, 0x3fb8aa3b, v5
	v_exp_f32_e32 v5, v5
	v_mul_f32_e32 v2, v2, v32
	v_cvt_pk_bf16_f32 v2, v2, s0
	ds_write_b16 v54, v2 offset:1280
	v_mul_f32_e32 v1, v1, v5
	v_mul_f32_e32 v2, 0x3fb8aa3b, v33
	v_mul_f32_e32 v5, 0x3fb8aa3b, v48
	v_exp_f32_e32 v2, v2
	v_exp_f32_e32 v5, v5
	v_cvt_pk_bf16_f32 v1, v1, s0
	ds_write_b16 v54, v1 offset:21760
	v_sub_f32_e32 v1, 1.0, v2
	v_mul_f32_e32 v2, v5, v17
	v_cvt_pk_bf16_f32 v2, v2, s0
	ds_write_b16 v54, v2 offset:1440
	v_sub_f32_e32 v2, v53, v48
	v_mul_f32_e32 v2, 0x3fb8aa3b, v2
	v_exp_f32_e32 v5, v2
	v_mul_f32_e32 v2, 0x3fb8aa3b, v34
	v_ashrrev_i32_e32 v15, 3, v0
	v_mov_b64_e32 v[10:11], s[0:1]
	v_exp_f32_e32 v14, v2
	v_lshlrev_b32_e32 v2, 4, v0
	v_mad_i64_i32 v[6:7], s[12:13], v15, s48, v[10:11]
	v_add_u32_e32 v12, 0x100, v0
	v_and_b32_e32 v2, 0x70, v2
	v_lshl_add_u64 v[6:7], v[6:7], 0, s[22:23]
	v_ashrrev_i32_e32 v17, 3, v12
	v_lshl_add_u64 v[6:7], v[6:7], 0, v[2:3]
	v_mad_i64_i32 v[10:11], s[12:13], v17, s48, v[10:11]
	s_waitcnt vmcnt(0)
	v_mov_b32_e32 v6, v140
	v_mov_b32_e32 v7, v141
	v_mov_b32_e32 v8, v142
	v_mov_b32_e32 v9, v143
	v_lshl_add_u64 v[10:11], v[10:11], 0, s[22:23]
	v_lshl_add_u64 v[10:11], v[10:11], 0, v[2:3]
	v_mov_b32_e32 v10, v144
	v_mov_b32_e32 v11, v145
	v_mov_b32_e32 v12, v146
	v_mov_b32_e32 v13, v147
	v_mul_f32_e32 v1, v1, v5
	v_cvt_pk_bf16_f32 v1, v1, s0
	v_mul_f32_e32 v5, 0x3fb8aa3b, v49
	ds_write_b16 v54, v1 offset:21920
	v_sub_f32_e32 v1, 1.0, v14
	v_exp_f32_e32 v5, v5
	v_sub_f32_e32 v14, v53, v49
	v_mul_f32_e32 v14, 0x3fb8aa3b, v14
	v_exp_f32_e32 v14, v14
	v_mul_f32_e32 v5, v5, v16
	v_cvt_pk_bf16_f32 v5, v5, s0
	ds_write_b16 v54, v5 offset:1600
	v_mul_f32_e32 v1, v1, v14
	v_mul_f32_e32 v5, 0x3fb8aa3b, v35
	v_mul_f32_e32 v14, 0x3fb8aa3b, v50
	v_exp_f32_e32 v5, v5
	v_exp_f32_e32 v14, v14
	v_cvt_pk_bf16_f32 v1, v1, s0
	ds_write_b16 v54, v1 offset:22080
	v_sub_f32_e32 v1, 1.0, v5
	v_mul_f32_e32 v5, v14, v36
	v_sub_f32_e32 v14, v53, v50
	v_mul_f32_e32 v14, 0x3fb8aa3b, v14
	v_cvt_pk_bf16_f32 v5, v5, s0
	v_exp_f32_e32 v14, v14
	ds_write_b16 v54, v5 offset:1760
	v_mul_f32_e32 v5, 0x3fb8aa3b, v37
	v_exp_f32_e32 v5, v5
	v_mul_f32_e32 v1, v1, v14
	v_cvt_pk_bf16_f32 v1, v1, s0
	ds_write_b16 v54, v1 offset:22240
	v_sub_f32_e32 v1, 1.0, v5
	v_mul_f32_e32 v5, 0x3fb8aa3b, v51
	v_exp_f32_e32 v5, v5
	v_sub_f32_e32 v14, v53, v51
	v_mul_f32_e32 v14, 0x3fb8aa3b, v14
	v_exp_f32_e32 v14, v14
	v_mul_f32_e32 v5, v5, v38
	v_cvt_pk_bf16_f32 v5, v5, s0
	ds_write_b16 v54, v5 offset:1920
	v_mul_f32_e32 v1, v1, v14
	v_mul_f32_e32 v5, 0x3fb8aa3b, v39
	v_mul_f32_e32 v14, 0x3fb8aa3b, v52
	v_exp_f32_e32 v5, v5
	v_exp_f32_e32 v14, v14
	v_cvt_pk_bf16_f32 v1, v1, s0
	ds_write_b16 v54, v1 offset:22400
	v_sub_f32_e32 v1, 1.0, v5
	v_mul_f32_e32 v5, v14, v41
	v_sub_f32_e32 v14, v53, v52
	v_mul_f32_e32 v14, 0x3fb8aa3b, v14
	v_cvt_pk_bf16_f32 v5, v5, s0
	v_exp_f32_e32 v14, v14
	ds_write_b16 v54, v5 offset:2080
	v_mul_f32_e32 v5, 0x3fb8aa3b, v40
	v_exp_f32_e32 v5, v5
	v_mul_f32_e32 v1, v1, v14
	v_cvt_pk_bf16_f32 v1, v1, s0
	ds_write_b16 v54, v1 offset:22560
	v_sub_f32_e32 v1, 1.0, v5
	v_mul_f32_e32 v5, 0x3fb8aa3b, v53
	v_exp_f32_e32 v14, v5
	v_sub_f32_e32 v5, v53, v53
	v_mul_f32_e32 v5, 0x3fb8aa3b, v5
	v_exp_f32_e32 v5, v5
	v_mul_f32_e32 v16, v14, v42
	v_add_u32_e32 v2, 32, v2
	s_movk_i32 s8, 0xa0
	v_mul_f32_e32 v1, v1, v5
	v_lshl_add_u32 v5, v0, 2, 32
	v_cvt_pk_bf16_f32 v16, v16, s0
	v_cvt_pk_bf16_f32 v1, v1, s0
	ds_write_b32 v5, v14 offset:40960
	v_mad_u64_u32 v[14:15], s[12:13], v15, s8, v[2:3]
	ds_write_b16 v54, v16 offset:2240
	ds_write_b16 v54, v1 offset:22720
	s_waitcnt vmcnt(1)
	ds_write_b128 v14, v[6:9] offset:30720
	v_mad_u64_u32 v[6:7], s[12:13], v17, s8, v[2:3]
	s_mul_i32 s12, s11, 0x44
	s_waitcnt vmcnt(0)
	ds_write_b128 v6, v[10:13] offset:30720
	s_waitcnt lgkmcnt(0)
	s_barrier
	s_and_saveexec_b64 s[4:5], vcc
	s_xor_b64 s[4:5], exec, s[4:5]
	s_add_i32 s13, s12, s7
	s_or_saveexec_b64 s[4:5], s[4:5]
	v_mov_b32_e32 v1, s13
	s_xor_b64 exec, exec, s[4:5]
	s_cbranch_execz .LBB0_556
	ds_read2st64_b32 v[6:7], v5 offset0:160 offset1:161
	s_add_i32 s22, s12, s7
	s_lshl_b32 s12, s22, 8
	v_readlane_b32 s8, v252, 9
	s_add_u32 s12, s8, s12
	s_waitcnt lgkmcnt(0)
	v_mul_f32_e32 v2, v6, v7
	ds_read2st64_b32 v[6:7], v5 offset0:162 offset1:163
	v_readlane_b32 s8, v252, 10
	v_ashrrev_i32_e32 v1, 31, v0
	s_addc_u32 s13, s8, 0
	s_waitcnt lgkmcnt(0)
	v_mul_f32_e32 v2, v2, v6
	v_mul_f32_e32 v2, v2, v7
	v_lshl_add_u64 v[6:7], v[0:1], 2, s[12:13]
	v_mov_b32_e32 v1, s22
	global_store_dword v[6:7], v2, off

.LBB0_561:
	s_and_b64 vcc, exec, s[0:1]
	s_cbranch_vccz .LBB0_718
	v_mov_b32_e32 v0, v222
	s_mul_i32 s0, s16, 0x1f00
	s_waitcnt vmcnt(11)
	v_mov_b32_e32 v30, v3
	v_add_u32_e32 v4, s0, v0
	v_add_u32_e32 v14, 0x400, v4
	v_add_u32_e32 v16, 0x500, v4
	v_add_u32_e32 v18, 0x600, v4
	v_add_u32_e32 v20, 0x700, v4
	v_ashrrev_i32_e32 v5, 31, v4
	v_add_u32_e32 v8, 0x100, v4
	v_add_u32_e32 v10, 0x200, v4
	v_add_u32_e32 v12, 0x300, v4
	v_ashrrev_i32_e32 v15, 31, v14
	v_ashrrev_i32_e32 v17, 31, v16
	v_ashrrev_i32_e32 v19, 31, v18
	v_ashrrev_i32_e32 v21, 31, v20
	v_lshl_add_u64 v[6:7], v[4:5], 2, s[74:75]
	v_ashrrev_i32_e32 v9, 31, v8
	v_ashrrev_i32_e32 v11, 31, v10
	v_ashrrev_i32_e32 v13, 31, v12
	v_lshl_add_u64 v[14:15], v[14:15], 2, s[74:75]
	v_lshl_add_u64 v[16:17], v[16:17], 2, s[74:75]
	v_lshl_add_u64 v[18:19], v[18:19], 2, s[74:75]
	v_lshl_add_u64 v[20:21], v[20:21], 2, s[74:75]
	v_lshl_add_u64 v[8:9], v[8:9], 2, s[74:75]
	v_lshl_add_u64 v[10:11], v[10:11], 2, s[74:75]
	v_lshl_add_u64 v[12:13], v[12:13], 2, s[74:75]
	global_load_dword v60, v[6:7], off
	global_load_dword v61, v[8:9], off
	global_load_dword v62, v[10:11], off
	global_load_dword v63, v[12:13], off
	global_load_dword v64, v[14:15], off
	global_load_dword v65, v[16:17], off
	global_load_dword v66, v[18:19], off
	global_load_dword v67, v[20:21], off
	v_add_u32_e32 v14, 0x1000, v4
	v_add_u32_e32 v16, 0x1100, v4
	v_add_u32_e32 v18, 0x1200, v4
	v_add_u32_e32 v20, 0x1300, v4
	v_ashrrev_i32_e32 v15, 31, v14
	v_ashrrev_i32_e32 v17, 31, v16
	v_ashrrev_i32_e32 v19, 31, v18
	v_ashrrev_i32_e32 v21, 31, v20
	v_add_u32_e32 v22, 0x1400, v4
	v_add_u32_e32 v24, 0x1500, v4
	v_add_u32_e32 v26, 0x1600, v4
	v_add_u32_e32 v28, 0x1700, v4
	v_lshl_add_u64 v[14:15], v[14:15], 2, s[74:75]
	v_lshl_add_u64 v[16:17], v[16:17], 2, s[74:75]
	v_lshl_add_u64 v[18:19], v[18:19], 2, s[74:75]
	v_lshl_add_u64 v[20:21], v[20:21], 2, s[74:75]
	v_ashrrev_i32_e32 v23, 31, v22
	v_ashrrev_i32_e32 v25, 31, v24
	v_ashrrev_i32_e32 v27, 31, v26
	v_ashrrev_i32_e32 v29, 31, v28
	v_lshl_add_u64 v[22:23], v[22:23], 2, s[74:75]
	v_lshl_add_u64 v[24:25], v[24:25], 2, s[74:75]
	v_lshl_add_u64 v[26:27], v[26:27], 2, s[74:75]
	v_lshl_add_u64 v[28:29], v[28:29], 2, s[74:75]
	global_load_dword v68, v[14:15], off
	global_load_dword v69, v[16:17], off
	global_load_dword v70, v[18:19], off
	global_load_dword v36, v[20:21], off
	global_load_dword v37, v[22:23], off
	global_load_dword v38, v[24:25], off
	global_load_dword v39, v[26:27], off
	global_load_dword v40, v[28:29], off
	v_add_u32_e32 v14, 0x1800, v4
	v_add_u32_e32 v16, 0x1900, v4
	v_add_u32_e32 v18, 0x1a00, v4
	v_add_u32_e32 v20, 0x1b00, v4
	v_ashrrev_i32_e32 v15, 31, v14
	v_ashrrev_i32_e32 v17, 31, v16
	v_ashrrev_i32_e32 v19, 31, v18
	v_ashrrev_i32_e32 v21, 31, v20
	v_add_u32_e32 v22, 0x1c00, v4
	v_add_u32_e32 v6, 0x800, v4
	v_lshl_add_u64 v[14:15], v[14:15], 2, s[74:75]
	v_lshl_add_u64 v[16:17], v[16:17], 2, s[74:75]
	v_lshl_add_u64 v[18:19], v[18:19], 2, s[74:75]
	v_lshl_add_u64 v[20:21], v[20:21], 2, s[74:75]
	v_ashrrev_i32_e32 v23, 31, v22
	v_ashrrev_i32_e32 v7, 31, v6
	v_add_u32_e32 v8, 0x900, v4
	v_add_u32_e32 v10, 0xa00, v4
	v_add_u32_e32 v12, 0xb00, v4
	v_lshl_add_u64 v[22:23], v[22:23], 2, s[74:75]
	global_load_dword v41, v[14:15], off
	global_load_dword v42, v[16:17], off
	global_load_dword v43, v[18:19], off
	global_load_dword v44, v[20:21], off
	global_load_dword v45, v[22:23], off
	v_add_u32_e32 v14, 0xc00, v4
	v_add_u32_e32 v16, 0xd00, v4
	v_add_u32_e32 v18, 0xe00, v4
	v_add_u32_e32 v20, 0xf00, v4
	v_lshl_add_u64 v[6:7], v[6:7], 2, s[74:75]
	v_ashrrev_i32_e32 v9, 31, v8
	v_ashrrev_i32_e32 v11, 31, v10
	v_ashrrev_i32_e32 v13, 31, v12
	v_ashrrev_i32_e32 v15, 31, v14
	v_ashrrev_i32_e32 v17, 31, v16
	v_ashrrev_i32_e32 v19, 31, v18
	v_ashrrev_i32_e32 v21, 31, v20
	v_lshl_add_u64 v[8:9], v[8:9], 2, s[74:75]
	v_lshl_add_u64 v[10:11], v[10:11], 2, s[74:75]
	v_lshl_add_u64 v[12:13], v[12:13], 2, s[74:75]
	v_lshl_add_u64 v[14:15], v[14:15], 2, s[74:75]
	v_lshl_add_u64 v[16:17], v[16:17], 2, s[74:75]
	v_lshl_add_u64 v[18:19], v[18:19], 2, s[74:75]
	v_lshl_add_u64 v[20:21], v[20:21], 2, s[74:75]
	global_load_dword v71, v[6:7], off
	global_load_dword v72, v[8:9], off
	global_load_dword v73, v[10:11], off
	global_load_dword v74, v[12:13], off
	global_load_dword v75, v[14:15], off
	global_load_dword v76, v[16:17], off
	global_load_dword v77, v[18:19], off
	global_load_dword v78, v[20:21], off
	v_add_u32_e32 v6, 0x1d00, v4
	v_add_u32_e32 v4, 0x1e00, v4
	v_ashrrev_i32_e32 v7, 31, v6
	v_ashrrev_i32_e32 v5, 31, v4
	v_lshl_add_u64 v[6:7], v[6:7], 2, s[74:75]
	v_lshl_add_u64 v[4:5], v[4:5], 2, s[74:75]
	v_readlane_b32 s0, v252, 40
	global_load_dword v46, v[6:7], off
	global_load_dword v47, v[4:5], off
	v_add_u32_e32 v4, s0, v0
	v_ashrrev_i32_e32 v5, 31, v4
	v_lshl_add_u64 v[4:5], v[4:5], 2, s[76:77]
	global_load_dword v79, v[4:5], off
	v_readlane_b32 s1, v252, 41
	s_add_i32 s0, s6, 0xf9a0
	s_and_b32 s1, s0, 0xffff
	s_mul_i32 s1, s1, 0xf0f1
	s_lshr_b32 s1, s1, 22
	s_mul_i32 s4, s1, 0x44
	s_sub_i32 s0, s0, s4
	s_and_b32 s4, s0, 0xffff
	s_lshl_b32 s10, s0, 6
	s_cmp_lt_u32 s4, 4
	s_mul_i32 s0, s1, 0x1100
	s_movk_i32 s1, 0x1100
	v_ashrrev_i32_e32 v1, 31, v0
	v_mov_b32_e32 v4, v3
	v_mov_b32_e32 v5, v3
	v_mov_b32_e32 v6, v3
	v_mov_b32_e32 v7, v3
	v_mov_b32_e32 v8, v3
	v_mov_b32_e32 v9, v3
	v_mov_b32_e32 v10, v3
	v_mov_b32_e32 v11, v3
	v_mov_b32_e32 v12, v3
	v_mov_b32_e32 v13, v3
	v_mov_b32_e32 v14, v3
	v_mov_b32_e32 v15, v3
	v_mov_b32_e32 v16, v3
	v_mov_b32_e32 v17, v3
	v_mov_b32_e32 v18, v3
	v_mov_b32_e32 v19, v3
	v_mov_b32_e32 v20, v3
	v_mov_b32_e32 v21, v3
	v_mov_b32_e32 v22, v3
	v_mov_b32_e32 v23, v3
	v_mov_b32_e32 v24, v3
	v_mov_b32_e32 v25, v3
	v_mov_b32_e32 v26, v3
	v_mov_b32_e32 v27, v3
	v_mov_b32_e32 v28, v3
	v_mov_b32_e32 v29, v3
	s_cselect_b32 s4, 0, 0x100
	s_cselect_b32 s7, 0x100, s1
	s_and_b32 s1, s10, 0xffc0
	s_waitcnt vmcnt(40)
	v_lshl_add_u64 v[48:49], v[0:1], 1, s[24:25]
	v_mov_b32_e32 v1, v3
	v_mov_b32_e32 v2, v3
	v_mov_b64_e32 v[34:35], v[30:31]
	s_mov_b32 s5, 0
	s_add_i32 s10, s1, -15
	s_waitcnt vmcnt(19)
	v_mov_b32_e32 v50, v37
	v_mov_b32_e32 v51, v36
	s_waitcnt vmcnt(17)
	v_mov_b32_e32 v52, v39
	v_mov_b32_e32 v53, v38
	s_waitcnt vmcnt(15)
	v_mov_b32_e32 v54, v41
	v_mov_b32_e32 v55, v40
	s_waitcnt vmcnt(13)
	v_mov_b32_e32 v56, v43
	v_mov_b32_e32 v57, v42
	s_waitcnt vmcnt(11)
	v_mov_b32_e32 v58, v45
	v_mov_b32_e32 v59, v44
	s_and_b32 s11, s0, 0xff00
	v_mov_b64_e32 v[32:33], v[28:29]
	v_mov_b64_e32 v[30:31], v[26:27]
	v_mov_b64_e32 v[28:29], v[24:25]
	v_mov_b64_e32 v[26:27], v[22:23]
	v_mov_b64_e32 v[24:25], v[20:21]
	v_mov_b64_e32 v[22:23], v[18:19]
	v_mov_b64_e32 v[20:21], v[16:17]
	v_mov_b64_e32 v[18:19], v[14:15]
	v_mov_b64_e32 v[16:17], v[12:13]
	v_mov_b64_e32 v[14:15], v[10:11]
	v_mov_b64_e32 v[12:13], v[8:9]
	v_mov_b64_e32 v[10:11], v[6:7]
	v_mov_b64_e32 v[8:9], v[4:5]
	v_mov_b64_e32 v[6:7], v[2:3]
	v_mov_b64_e32 v[4:5], v[0:1]
	s_add_i32 s98, s5, s10
	s_add_i32 s98, s98, s11
	v_add_co_u32_e32 v208, vcc, 0x800, v48
	s_nop 1
	v_addc_co_u32_e32 v209, vcc, 0, v49, vcc
	s_max_i32 s99, s98, 0
	v_mad_u64_u32 v[210:211], s[42:43], s99, v233, v[208:209]
	global_load_ushort v84, v[210:211], off offset:2048
	global_load_ushort v115, v[210:211], off offset:1536
	s_add_i32 s98, s98, 1
	s_max_i32 s99, s98, 0
	v_mad_u64_u32 v[212:213], s[42:43], s99, v233, v[208:209]
	global_load_ushort v85, v[212:213], off offset:2048
	global_load_ushort v116, v[212:213], off offset:1536
	s_add_i32 s98, s98, 1
	s_max_i32 s99, s98, 0
	v_mad_u64_u32 v[210:211], s[42:43], s99, v233, v[208:209]
	global_load_ushort v86, v[210:211], off offset:2048
	global_load_ushort v117, v[210:211], off offset:1536
	s_add_i32 s98, s98, 1
	s_max_i32 s99, s98, 0
	v_mad_u64_u32 v[212:213], s[42:43], s99, v233, v[208:209]
	global_load_ushort v87, v[212:213], off offset:2048
	global_load_ushort v118, v[212:213], off offset:1536
	s_add_i32 s98, s98, 1
	s_max_i32 s99, s98, 0
	v_mad_u64_u32 v[210:211], s[42:43], s99, v233, v[208:209]
	global_load_ushort v88, v[210:211], off offset:2048
	global_load_ushort v119, v[210:211], off offset:1536
	s_add_i32 s98, s98, 1
	s_max_i32 s99, s98, 0
	v_mad_u64_u32 v[212:213], s[42:43], s99, v233, v[208:209]
	global_load_ushort v89, v[212:213], off offset:2048
	global_load_ushort v120, v[212:213], off offset:1536
	s_add_i32 s98, s98, 1
	s_max_i32 s99, s98, 0
	v_mad_u64_u32 v[210:211], s[42:43], s99, v233, v[208:209]
	global_load_ushort v90, v[210:211], off offset:2048
	global_load_ushort v121, v[210:211], off offset:1536
	s_add_i32 s98, s98, 1
	s_max_i32 s99, s98, 0
	v_mad_u64_u32 v[212:213], s[42:43], s99, v233, v[208:209]
	global_load_ushort v91, v[212:213], off offset:2048
	global_load_ushort v122, v[212:213], off offset:1536
	s_add_i32 s98, s98, 1
	s_max_i32 s99, s98, 0
	v_mad_u64_u32 v[210:211], s[42:43], s99, v233, v[208:209]
	global_load_ushort v92, v[210:211], off offset:2048
	global_load_ushort v123, v[210:211], off offset:1536
	s_add_i32 s98, s98, 1
	s_max_i32 s99, s98, 0
	v_mad_u64_u32 v[212:213], s[42:43], s99, v233, v[208:209]
	global_load_ushort v93, v[212:213], off offset:2048
	global_load_ushort v124, v[212:213], off offset:1536
	s_add_i32 s98, s98, 1
	s_max_i32 s99, s98, 0
	v_mad_u64_u32 v[210:211], s[42:43], s99, v233, v[208:209]
	global_load_ushort v94, v[210:211], off offset:2048
	global_load_ushort v125, v[210:211], off offset:1536
	s_add_i32 s98, s98, 1
	s_max_i32 s99, s98, 0
	v_mad_u64_u32 v[212:213], s[42:43], s99, v233, v[208:209]
	global_load_ushort v95, v[212:213], off offset:2048
	global_load_ushort v126, v[212:213], off offset:1536
	s_add_i32 s98, s98, 1
	s_max_i32 s99, s98, 0
	v_mad_u64_u32 v[210:211], s[42:43], s99, v233, v[208:209]
	global_load_ushort v96, v[210:211], off offset:2048
	global_load_ushort v127, v[210:211], off offset:1536
	s_add_i32 s98, s98, 1
	s_max_i32 s99, s98, 0
	v_mad_u64_u32 v[212:213], s[42:43], s99, v233, v[208:209]
	global_load_ushort v97, v[212:213], off offset:2048
	global_load_ushort v128, v[212:213], off offset:1536
	s_add_i32 s98, s98, 1
	s_max_i32 s99, s98, 0
	v_mad_u64_u32 v[210:211], s[42:43], s99, v233, v[208:209]
	global_load_ushort v98, v[210:211], off offset:2048
	global_load_ushort v129, v[210:211], off offset:1536
	s_add_i32 s98, s98, 1
	s_max_i32 s99, s98, 0
	v_mad_u64_u32 v[212:213], s[42:43], s99, v233, v[208:209]
	global_load_ushort v99, v[212:213], off offset:2048
	global_load_ushort v130, v[212:213], off offset:1536
	s_add_i32 s98, s98, 1
	s_max_i32 s99, s98, 0
	v_mad_u64_u32 v[210:211], s[42:43], s99, v233, v[208:209]
	global_load_ushort v100, v[210:211], off offset:2048
	global_load_ushort v131, v[210:211], off offset:1536
	s_add_i32 s98, s98, 1
	s_max_i32 s99, s98, 0
	v_mad_u64_u32 v[212:213], s[42:43], s99, v233, v[208:209]
	global_load_ushort v101, v[212:213], off offset:2048
	global_load_ushort v132, v[212:213], off offset:1536
	s_add_i32 s98, s98, 1
	s_max_i32 s99, s98, 0
	v_mad_u64_u32 v[210:211], s[42:43], s99, v233, v[208:209]
	global_load_ushort v102, v[210:211], off offset:2048
	global_load_ushort v133, v[210:211], off offset:1536
	s_add_i32 s98, s98, 1
	s_max_i32 s99, s98, 0
	v_mad_u64_u32 v[212:213], s[42:43], s99, v233, v[208:209]
	global_load_ushort v103, v[212:213], off offset:2048
	global_load_ushort v134, v[212:213], off offset:1536
	s_add_i32 s98, s98, 1
	s_max_i32 s99, s98, 0
	v_mad_u64_u32 v[210:211], s[42:43], s99, v233, v[208:209]
	global_load_ushort v104, v[210:211], off offset:2048
	global_load_ushort v135, v[210:211], off offset:1536
	s_add_i32 s98, s98, 1
	s_max_i32 s99, s98, 0
	v_mad_u64_u32 v[212:213], s[42:43], s99, v233, v[208:209]
	global_load_ushort v105, v[212:213], off offset:2048
	global_load_ushort v136, v[212:213], off offset:1536
	s_add_i32 s98, s98, 1
	s_max_i32 s99, s98, 0
	v_mad_u64_u32 v[210:211], s[42:43], s99, v233, v[208:209]
	global_load_ushort v106, v[210:211], off offset:2048
	global_load_ushort v137, v[210:211], off offset:1536
	s_add_i32 s98, s98, 1
	s_max_i32 s99, s98, 0
	v_mad_u64_u32 v[212:213], s[42:43], s99, v233, v[208:209]
	global_load_ushort v107, v[212:213], off offset:2048
	global_load_ushort v138, v[212:213], off offset:1536
	s_add_i32 s98, s98, 1
	s_max_i32 s99, s98, 0
	v_mad_u64_u32 v[210:211], s[42:43], s99, v233, v[208:209]
	global_load_ushort v108, v[210:211], off offset:2048
	global_load_ushort v139, v[210:211], off offset:1536
	s_add_i32 s98, s98, 1
	s_max_i32 s99, s98, 0
	v_mad_u64_u32 v[212:213], s[42:43], s99, v233, v[208:209]
	global_load_ushort v109, v[212:213], off offset:2048
	global_load_ushort v140, v[212:213], off offset:1536
	s_add_i32 s98, s98, 1
	s_max_i32 s99, s98, 0
	v_mad_u64_u32 v[210:211], s[42:43], s99, v233, v[208:209]
	global_load_ushort v110, v[210:211], off offset:2048
	global_load_ushort v141, v[210:211], off offset:1536
	s_add_i32 s98, s98, 1
	s_max_i32 s99, s98, 0
	v_mad_u64_u32 v[212:213], s[42:43], s99, v233, v[208:209]
	global_load_ushort v111, v[212:213], off offset:2048
	global_load_ushort v142, v[212:213], off offset:1536
	s_add_i32 s98, s98, 1
	s_max_i32 s99, s98, 0
	v_mad_u64_u32 v[210:211], s[42:43], s99, v233, v[208:209]
	global_load_ushort v112, v[210:211], off offset:2048
	global_load_ushort v143, v[210:211], off offset:1536
	s_add_i32 s98, s98, 1
	s_max_i32 s99, s98, 0
	v_mad_u64_u32 v[212:213], s[42:43], s99, v233, v[208:209]
	global_load_ushort v113, v[212:213], off offset:2048
	global_load_ushort v144, v[212:213], off offset:1536
	s_add_i32 s98, s98, 1
	s_max_i32 s99, s98, 0
	v_mad_u64_u32 v[210:211], s[42:43], s99, v233, v[208:209]
	global_load_ushort v114, v[210:211], off offset:2048
	global_load_ushort v145, v[210:211], off offset:1536
	s_add_i32 s98, s98, 1

.LBB0_719:
	s_andn2_b64 vcc, exec, s[0:1]
	s_cbranch_vccnz .LBB0_759
	v_mov_b32_e32 v0, v222
	s_nop 0
	v_lshlrev_b32_e32 v1, 2, v0
	s_waitcnt vmcnt(8)
	v_and_b32_e32 v64, 0xfc, v1
	v_lshlrev_b32_e32 v1, 2, v64
	global_load_dwordx4 v[20:23], v1, s[52:53]
	global_load_dwordx4 v[16:19], v1, s[52:53] offset:1024
	global_load_dwordx4 v[12:15], v1, s[52:53] offset:2048
	global_load_dwordx4 v[8:11], v1, s[52:53] offset:3072
	global_load_dwordx4 v[4:7], v1, s[56:57]
	s_add_i32 s0, s6, 0xfbc0
	s_and_b32 s1, s0, 0xffff
	s_mul_i32 s1, s1, 0xf0f1
	s_lshr_b32 s4, s1, 22
	s_mul_i32 s1, s4, 0x44
	s_sub_i32 s0, s0, s1
	s_and_b32 s5, s0, 0xffff
	v_ashrrev_i32_e32 v62, 2, v0
	s_cmp_lt_u32 s5, 4
	s_movk_i32 s0, 0x1100
	v_and_b32_e32 v63, -16, v62
	s_cselect_b32 s10, 0x100, s0
	s_cselect_b32 s11, 0, 0x100
	v_lshl_add_u32 v24, s5, 6, v63
	v_lshlrev_b32_e32 v2, 1, v64
	v_cmp_lt_i32_e32 vcc, s11, v24
	v_cmp_ge_i32_e64 s[0:1], s10, v24
	s_mul_i32 s7, s4, 0x1100
	v_add_u32_e32 v25, -2, v24
	v_lshl_add_u64 v[0:1], s[24:25], 0, v[2:3]
	s_and_b64 s[12:13], vcc, s[0:1]
	v_mov_b64_e32 v[36:37], 0
	v_mov_b64_e32 v[46:47], 0
	s_and_saveexec_b64 s[0:1], s[12:13]
	s_cbranch_execz .LBB0_722
	v_add_u32_e32 v2, s7, v25
	v_mad_u64_u32 v[26:27], s[12:13], v2, s48, v[0:1]
	global_load_dwordx2 v[46:47], v[26:27], off

.LBB0_765:
	s_mul_i32 s0, s36, 0x1dc0000
	s_mul_hi_i32 s1, s36, 0x1dc0000
	s_add_u32 s0, s24, s0
	s_addc_u32 s1, s25, s1
	s_lshl_b32 s6, s4, 6
	s_and_b32 s33, s6, 0xc0
	s_lshl_b32 s22, s33, 1
	s_cmp_lt_u32 s5, 2
	v_mov_b32_e32 v18, v222
	s_cselect_b32 s38, 4, 0x44
	v_lshlrev_b32_e32 v0, 4, v18
	s_add_u32 s6, s0, s22
	v_and_b32_e32 v4, 0x70, v0
	v_mov_b32_e32 v5, v3
	s_addc_u32 s7, s1, 0
	v_lshl_add_u64 v[0:1], s[6:7], 0, v[4:5]
	s_mov_b64 s[6:7], 0x1600
	v_ashrrev_i32_e32 v19, 3, v18
	v_lshl_add_u64 v[6:7], v[0:1], 0, s[6:7]
	s_mov_b64 s[6:7], 0x1800
	v_lshl_add_u64 v[0:1], v[0:1], 0, s[6:7]
	v_add_u32_e32 v2, 32, v19
	v_mad_i64_i32 v[10:11], s[6:7], v19, s48, v[0:1]
	v_mad_i64_i32 v[12:13], s[6:7], v2, s48, v[0:1]
	v_ashrrev_i32_e32 v0, 1, v18
	v_and_b32_e32 v0, 0xffffffe0, v0
	v_and_b32_e32 v5, 31, v18
	v_lshl_add_u32 v0, s5, 7, v0
	v_or_b32_e32 v148, v0, v5
	v_mov_b64_e32 v[0:1], s[0:1]
	v_bfe_u32 v219, v18, 5, 1
	v_mad_i64_i32 v[0:1], s[0:1], v148, s48, v[0:1]
	v_mad_i64_i32 v[8:9], s[6:7], v19, s48, v[6:7]
	v_mad_i64_i32 v[6:7], s[6:7], v2, s48, v[6:7]
	v_lshl_add_u64 v[14:15], v[0:1], 0, s[22:23]
	v_lshlrev_b32_e32 v2, 4, v219
	v_lshl_add_u64 v[14:15], v[14:15], 0, v[2:3]
	s_mov_b64 s[0:1], 0x1400
	v_lshl_add_u64 v[16:17], v[14:15], 0, s[0:1]
	s_movk_i32 s0, 0x1000
	v_add_co_u32_e32 v14, vcc, s0, v14
	s_mov_b32 s0, 0x70000
	s_nop 0
	v_addc_co_u32_e32 v15, vcc, 0, v15, vcc
	global_load_dwordx4 v[100:103], v[8:9], off
	global_load_dwordx4 v[104:107], v[6:7], off
	v_add_co_u32_e32 v8, vcc, s0, v8
	global_load_dwordx4 v[112:115], v[10:11], off
	global_load_dwordx4 v[128:131], v[12:13], off
	v_addc_co_u32_e32 v9, vcc, 0, v9, vcc
	v_add_co_u32_e32 v6, vcc, s0, v6
	global_load_dwordx4 v[108:111], v[16:17], off offset:32
	global_load_dwordx4 v[116:119], v[16:17], off offset:64
	global_load_dwordx4 v[120:123], v[14:15], off offset:1024
	global_load_dwordx4 v[124:127], v[16:17], off offset:96
	v_addc_co_u32_e32 v7, vcc, 0, v7, vcc
	global_load_dwordx4 v[132:135], v[8:9], off
	global_load_dwordx4 v[136:139], v[6:7], off
	v_add_co_u32_e32 v6, vcc, s0, v10
	v_mul_u32_u24_e32 v5, 0x48, v5
	s_nop 0
	v_addc_co_u32_e32 v7, vcc, 0, v11, vcc
	v_add_co_u32_e32 v8, vcc, s0, v12
	s_movk_i32 s0, 0x90
	s_nop 0
	v_addc_co_u32_e32 v9, vcc, 0, v13, vcc
	global_load_dwordx4 v[140:143], v[6:7], off
	global_load_dwordx4 v[144:147], v[8:9], off
	v_lshrrev_b32_e32 v6, 3, v18
	v_bfe_u32 v7, v18, 2, 2
	v_mul_lo_u32 v9, v19, s0
	v_and_b32_e32 v8, 16, v18
	v_and_or_b32 v6, v6, 4, v7
	v_add3_u32 v239, 32, v9, v4
	v_lshlrev_b32_e32 v4, 2, v18
	v_lshlrev_b32_e32 v5, 1, v5
	v_and_or_b32 v4, v4, 12, v8
	v_add3_u32 v240, 32, v5, v2
	v_mul_u32_u24_e32 v5, 0x48, v6
	v_lshlrev_b32_e32 v4, 1, v4
	v_lshlrev_b32_e32 v5, 1, v5
	v_add3_u32 v241, 32, v4, v5
	v_add3_u32 v242, 32, v5, v4
	v_mad_i64_i32 v[4:5], s[0:1], v19, s48, 0
	v_mad_i64_i32 v[4:5], s[0:1], s36, v237, v[4:5]
	s_and_b32 s0, s4, 3
	v_and_b32_e32 v6, 7, v18
	s_lshl_b32 s0, s0, 7
	v_lshlrev_b32_e32 v6, 4, v6
	v_or3_b32 v4, v4, s0, v6
	v_mov_b32_e32 v18, v3
	v_mov_b32_e32 v19, v3
	v_lshl_add_u64 v[150:151], s[30:31], 0, v[4:5]
	v_mov_b32_e32 v4, v3
	v_mov_b32_e32 v5, v3
	v_mov_b32_e32 v6, v3
	v_mov_b32_e32 v7, v3
	v_mov_b32_e32 v8, v3
	v_mov_b32_e32 v9, v3
	v_mov_b32_e32 v10, v3
	v_mov_b32_e32 v11, v3
	v_mov_b32_e32 v12, v3
	v_mov_b32_e32 v13, v3
	v_mov_b32_e32 v14, v3
	v_mov_b32_e32 v15, v3
	v_mov_b32_e32 v16, v3
	v_mov_b32_e32 v17, v3
	s_waitcnt vmcnt(22)
	v_mov_b64_e32 v[34:35], v[18:19]
	s_waitcnt vmcnt(20)
	v_mov_b64_e32 v[66:67], v[18:19]
	v_mov_b64_e32 v[50:51], v[18:19]
	s_mov_b32 s39, 0
	v_ashrrev_i32_e32 v149, 31, v148
	v_mov_b32_e32 v153, 0
	s_mov_b64 s[0:1], 0
	v_mov_b64_e32 v[32:33], v[16:17]
	v_mov_b64_e32 v[30:31], v[14:15]
	v_mov_b64_e32 v[28:29], v[12:13]
	v_mov_b64_e32 v[26:27], v[10:11]
	v_mov_b64_e32 v[24:25], v[8:9]
	v_mov_b64_e32 v[22:23], v[6:7]
	v_mov_b64_e32 v[20:21], v[4:5]
	v_mov_b32_e32 v152, 0
	v_mov_b32_e32 v243, 0
	v_mov_b32_e32 v244, 0
	v_mov_b64_e32 v[64:65], v[16:17]
	v_mov_b64_e32 v[62:63], v[14:15]
	v_mov_b64_e32 v[60:61], v[12:13]
	v_mov_b64_e32 v[58:59], v[10:11]
	v_mov_b64_e32 v[56:57], v[8:9]
	v_mov_b64_e32 v[54:55], v[6:7]
	v_mov_b64_e32 v[52:53], v[4:5]
	v_mov_b64_e32 v[48:49], v[16:17]
	v_mov_b64_e32 v[46:47], v[14:15]
	v_mov_b64_e32 v[44:45], v[12:13]
	v_mov_b64_e32 v[42:43], v[10:11]
	v_mov_b64_e32 v[40:41], v[8:9]
	v_mov_b64_e32 v[38:39], v[6:7]
	v_mov_b64_e32 v[36:37], v[4:5]
	s_waitcnt vmcnt(11)
	ds_write_b128 v239, v[100:103]
	s_waitcnt vmcnt(10)
	ds_write_b128 v239, v[104:107] offset:4608
	s_waitcnt vmcnt(9)
	ds_write_b128 v239, v[112:115] offset:18432
	s_waitcnt vmcnt(8)
	ds_write_b128 v239, v[128:131] offset:23040
	s_waitcnt lgkmcnt(0)
	s_barrier
	v_mov_b32_e32 v223, v219
	v_mov_b32_e32 v254, v239
	s_add_u32 s4, s0, 0x7275000
	s_addc_u32 s5, s1, 0
	s_add_u32 s6, s0, 0x72ad000
	s_addc_u32 s7, s1, 0
	v_lshl_add_u64 v[72:73], v[150:151], 0, s[4:5]
	v_lshl_add_u64 v[74:75], v[150:151], 0, s[6:7]
	global_load_dwordx4 v[100:103], v[72:73], off offset:1536
	global_load_dwordx4 v[112:115], v[72:73], off offset:2048
	global_load_dwordx4 v[104:107], v[74:75], off offset:1536
	global_load_dwordx4 v[128:131], v[74:75], off offset:2048
	v_mov_b32_e32 v224, 0
	v_mov_b32_e32 v225, 0
	v_mov_b32_e32 v226, 0
	v_mov_b32_e32 v227, 0
	v_mov_b32_e32 v228, 0
	v_mov_b32_e32 v229, 0
	v_mov_b32_e32 v230, 0
	v_mov_b32_e32 v231, 0
	v_mov_b32_e32 v232, 0
	v_mov_b32_e32 v233, 0
	v_mov_b32_e32 v234, 0
	v_mov_b32_e32 v235, 0
	v_mov_b32_e32 v236, 0
	v_mov_b32_e32 v237, 0
	v_mov_b32_e32 v238, 0
	v_mov_b32_e32 v239, 0
	v_mov_b32_e32 v244, 0
	v_mov_b32_e32 v245, 0
	v_mov_b32_e32 v246, 0
	v_mov_b32_e32 v247, 0
	v_mov_b32_e32 v248, 0
	v_mov_b32_e32 v249, 0
	v_mov_b32_e32 v250, 0
	v_mov_b32_e32 v251, 0
	v_mov_b32_e32 v243, 0
	v_lshrrev_b32_e32 v218, 4, v222
	v_xor_b32_e32 v218, v218, v222
	v_and_b32_e32 v218, 1, v218
	v_cmp_eq_u32_e32 vcc, 0, v218
	v_mov_b32_e32 v219, 0x3f803f80
	v_cndmask_b32_e32 v218, 0, v219, vcc
	v_mov_b32_e32 v219, v218
	v_mov_b32_e32 v220, v218
	v_mov_b32_e32 v221, v218
	ds_read_b128 v[186:189], v240
	ds_read_b128 v[190:193], v240 offset:32
	ds_read_b128 v[194:197], v240 offset:64
	ds_read_b128 v[198:201], v240 offset:96
	s_waitcnt vmcnt(4)
	ds_write_b128 v254, v[132:135] offset:9216
	ds_write_b128 v254, v[136:139] offset:13824
	ds_write_b128 v254, v[140:143] offset:27648
	ds_write_b128 v254, v[144:147] offset:32256
	s_waitcnt lgkmcnt(0)
	s_barrier
	s_add_u32 s4, s0, 0x72e5000
	s_addc_u32 s5, s1, 0
	s_add_u32 s6, s0, 0x731d000
	s_addc_u32 s7, s1, 0
	v_lshl_add_u64 v[72:73], v[150:151], 0, s[4:5]
	v_lshl_add_u64 v[74:75], v[150:151], 0, s[6:7]
	global_load_dwordx4 v[132:135], v[72:73], off offset:1536
	global_load_dwordx4 v[140:143], v[72:73], off offset:2048
	global_load_dwordx4 v[136:139], v[74:75], off offset:1536
	global_load_dwordx4 v[144:147], v[74:75], off offset:2048
	v_mfma_f32_32x32x16_bf16 v[68:83], v[186:189], v[120:123], v[224:239]
	v_mfma_f32_32x32x16_bf16 v[68:83], v[190:193], v[108:111], v[68:83]
	v_mfma_f32_32x32x16_bf16 v[154:169], v[194:197], v[116:119], v[224:239]
	v_mfma_f32_32x32x16_bf16 v[154:169], v[198:201], v[124:127], v[154:169]
	ds_read_b128 v[202:205], v240 offset:4608
	ds_read_b128 v[206:209], v240 offset:4640
	ds_read_b128 v[210:213], v240 offset:4672
	ds_read_b128 v[214:217], v240 offset:4704
	ds_read_b64_tr_b16 v[186:187], v241 offset:18432
	ds_read_b64_tr_b16 v[188:189], v241 offset:19584
	ds_read_b64_tr_b16 v[190:191], v241 offset:18496
	ds_read_b64_tr_b16 v[192:193], v241 offset:19648
	ds_read_b64_tr_b16 v[194:195], v241 offset:20736
	ds_read_b64_tr_b16 v[196:197], v241 offset:21888
	ds_read_b64_tr_b16 v[198:199], v241 offset:20800
	ds_read_b64_tr_b16 v[200:201], v241 offset:21952

.LBB0_902:
	s_or_b64 exec, exec, s[0:1]
	s_waitcnt lgkmcnt(0)
	s_barrier
	ds_read_b32 v0, v3 offset:16
	s_movk_i32 s0, 0xa9f
	s_waitcnt lgkmcnt(0)
	v_cmp_lt_i32_e32 vcc, s0, v0
	v_readfirstlane_b32 s10, v0
	s_mov_b64 s[0:1], -1
	s_cbranch_vccnz .LBB0_897
	s_cmpk_gt_i32 s10, 0x21f
	s_cbranch_scc0 .LBB0_913
	s_add_i32 s0, s10, 0xfde0
	s_and_b32 s1, s0, 0xffff
	s_mul_i32 s1, s1, 0xf0f1
	s_lshr_b32 s4, s1, 22
	s_mulk_i32 s4, 0x44
	s_sub_i32 s0, s0, s4
	s_and_b32 s4, s0, 0xffff
	s_lshr_b32 s5, s1, 24
	s_mul_i32 s11, s5, 0x1100
	s_lshl_b32 s0, s4, 6
	s_add_i32 s11, s11, s0
	s_mul_i32 s0, s11, 0x1c00
	s_bfe_u32 s6, s1, 0x20016
	s_waitcnt vmcnt(10)
	v_mov_b32_e32 v58, v222
	s_add_u32 s0, s24, s0
	v_mov_b32_e32 v8, v222
	s_addc_u32 s1, s25, 0
	s_lshl_b32 s33, s6, 6
	v_and_b32_e32 v0, 63, v8
	v_or_b32_e32 v1, s33, v0
	v_ashrrev_i32_e32 v9, 6, v8
	v_lshlrev_b32_e32 v2, 1, v1
	v_lshlrev_b32_e32 v11, 4, v9
	v_lshl_add_u64 v[4:5], s[0:1], 0, v[2:3]
	v_mad_i64_i32 v[6:7], s[8:9], v11, s48, v[4:5]
	v_mad_i64_i32 v[128:129], s[8:9], v11, s48, v[4:5]
	global_load_ushort v96, v[128:129], off offset:1024
	global_load_ushort v80, v[128:129], off offset:2048
	global_load_ushort v112, v[128:129], off offset:2560
	v_or_b32_e32 v137, 1, v11
	v_mad_i64_i32 v[130:131], s[8:9], v137, s48, v[4:5]
	global_load_ushort v97, v[130:131], off offset:1024
	global_load_ushort v81, v[130:131], off offset:2048
	global_load_ushort v113, v[130:131], off offset:2560
	v_or_b32_e32 v138, 2, v11
	v_mad_i64_i32 v[132:133], s[8:9], v138, s48, v[4:5]
	global_load_ushort v98, v[132:133], off offset:1024
	global_load_ushort v82, v[132:133], off offset:2048
	global_load_ushort v114, v[132:133], off offset:2560
	v_or_b32_e32 v139, 3, v11
	v_mad_i64_i32 v[134:135], s[8:9], v139, s48, v[4:5]
	global_load_ushort v99, v[134:135], off offset:1024
	global_load_ushort v83, v[134:135], off offset:2048
	global_load_ushort v115, v[134:135], off offset:2560
	v_or_b32_e32 v136, 4, v11
	v_mad_i64_i32 v[128:129], s[8:9], v136, s48, v[4:5]
	global_load_ushort v100, v[128:129], off offset:1024
	global_load_ushort v84, v[128:129], off offset:2048
	global_load_ushort v116, v[128:129], off offset:2560
	v_or_b32_e32 v137, 5, v11
	v_mad_i64_i32 v[130:131], s[8:9], v137, s48, v[4:5]
	global_load_ushort v101, v[130:131], off offset:1024
	global_load_ushort v85, v[130:131], off offset:2048
	global_load_ushort v117, v[130:131], off offset:2560
	v_or_b32_e32 v138, 6, v11
	v_mad_i64_i32 v[132:133], s[8:9], v138, s48, v[4:5]
	global_load_ushort v102, v[132:133], off offset:1024
	global_load_ushort v86, v[132:133], off offset:2048
	global_load_ushort v118, v[132:133], off offset:2560
	v_or_b32_e32 v139, 7, v11
	v_mad_i64_i32 v[134:135], s[8:9], v139, s48, v[4:5]
	global_load_ushort v103, v[134:135], off offset:1024
	global_load_ushort v87, v[134:135], off offset:2048
	global_load_ushort v119, v[134:135], off offset:2560
	v_or_b32_e32 v136, 8, v11
	v_mad_i64_i32 v[128:129], s[8:9], v136, s48, v[4:5]
	global_load_ushort v104, v[128:129], off offset:1024
	global_load_ushort v88, v[128:129], off offset:2048
	global_load_ushort v120, v[128:129], off offset:2560
	v_or_b32_e32 v137, 9, v11
	v_mad_i64_i32 v[130:131], s[8:9], v137, s48, v[4:5]
	global_load_ushort v105, v[130:131], off offset:1024
	global_load_ushort v89, v[130:131], off offset:2048
	global_load_ushort v121, v[130:131], off offset:2560
	v_or_b32_e32 v138, 10, v11
	v_mad_i64_i32 v[132:133], s[8:9], v138, s48, v[4:5]
	global_load_ushort v106, v[132:133], off offset:1024
	global_load_ushort v90, v[132:133], off offset:2048
	global_load_ushort v122, v[132:133], off offset:2560
	v_or_b32_e32 v139, 11, v11
	v_mad_i64_i32 v[134:135], s[8:9], v139, s48, v[4:5]
	global_load_ushort v107, v[134:135], off offset:1024
	global_load_ushort v91, v[134:135], off offset:2048
	global_load_ushort v123, v[134:135], off offset:2560
	v_or_b32_e32 v136, 12, v11
	v_mad_i64_i32 v[128:129], s[8:9], v136, s48, v[4:5]
	global_load_ushort v108, v[128:129], off offset:1024
	global_load_ushort v92, v[128:129], off offset:2048
	global_load_ushort v124, v[128:129], off offset:2560
	v_or_b32_e32 v137, 13, v11
	v_mad_i64_i32 v[130:131], s[8:9], v137, s48, v[4:5]
	global_load_ushort v109, v[130:131], off offset:1024
	global_load_ushort v93, v[130:131], off offset:2048
	global_load_ushort v125, v[130:131], off offset:2560
	v_or_b32_e32 v138, 14, v11
	v_mad_i64_i32 v[132:133], s[8:9], v138, s48, v[4:5]
	global_load_ushort v110, v[132:133], off offset:1024
	global_load_ushort v94, v[132:133], off offset:2048
	global_load_ushort v126, v[132:133], off offset:2560
	v_or_b32_e32 v139, 15, v11
	v_mad_i64_i32 v[134:135], s[8:9], v139, s48, v[4:5]
	global_load_ushort v111, v[134:135], off offset:1024
	global_load_ushort v95, v[134:135], off offset:2048
	global_load_ushort v127, v[134:135], off offset:2560
	v_lshrrev_b32_e32 v180, 3, v222
	v_mul_u32_u24_e32 v180, 0x1c00, v180
	v_lshlrev_b32_e32 v181, 4, v222
	v_and_b32_e32 v181, 0x70, v181
	s_lshl_b32 s99, s6, 7
	v_add3_u32 v180, v180, v181, s99
	global_load_dwordx4 v[140:143], v180, s[0:1] offset:1536
	v_add_u32_e32 v181, 0x38000, v180
	global_load_dwordx4 v[144:147], v181, s[0:1] offset:1536
	s_lshl_b32 s98, s5, 3
	s_lshl_b32 s99, s6, 1
	s_or_b32 s98, s98, s99
	s_mulk_i32 s98, 0x44
	s_add_i32 s98, s98, s4
	s_lshl_b32 s98, s98, 14
	s_add_u32 s98, s2, s98
	s_addc_u32 s99, s3, 0
	v_bfe_u32 v182, v222, 4, 2
	v_lshlrev_b32_e32 v182, 8, v182
	v_lshrrev_b32_e32 v183, 6, v222
	v_lshl_or_b32 v182, v183, 4, v182
	v_and_b32_e32 v183, 15, v222
	v_or_b32_e32 v182, v182, v183
	v_lshlrev_b32_e32 v182, 2, v182
	global_load_dword v148, v182, s[98:99] offset:0
	global_load_dword v149, v182, s[98:99] offset:256
	global_load_dword v150, v182, s[98:99] offset:512
	global_load_dword v151, v182, s[98:99] offset:768
	s_add_u32 s98, s98, 0x1000
	s_addc_u32 s99, s99, 0
	global_load_dword v152, v182, s[98:99] offset:0
	global_load_dword v153, v182, s[98:99] offset:256
	global_load_dword v154, v182, s[98:99] offset:512
	global_load_dword v155, v182, s[98:99] offset:768
	s_add_u32 s98, s98, 0x1000
	s_addc_u32 s99, s99, 0
	global_load_dword v156, v182, s[98:99] offset:0
	global_load_dword v157, v182, s[98:99] offset:256
	global_load_dword v158, v182, s[98:99] offset:512
	global_load_dword v159, v182, s[98:99] offset:768
	s_add_u32 s98, s98, 0x1000
	s_addc_u32 s99, s99, 0
	global_load_dword v160, v182, s[98:99] offset:0
	global_load_dword v161, v182, s[98:99] offset:256
	global_load_dword v162, v182, s[98:99] offset:512
	global_load_dword v163, v182, s[98:99] offset:768
	s_add_u32 s98, s98, 0x10d000
	s_addc_u32 s99, s99, 0
	global_load_dword v164, v182, s[98:99] offset:0
	global_load_dword v165, v182, s[98:99] offset:256
	global_load_dword v166, v182, s[98:99] offset:512
	global_load_dword v167, v182, s[98:99] offset:768
	s_add_u32 s98, s98, 0x1000
	s_addc_u32 s99, s99, 0
	global_load_dword v168, v182, s[98:99] offset:0
	global_load_dword v169, v182, s[98:99] offset:256
	global_load_dword v170, v182, s[98:99] offset:512
	global_load_dword v171, v182, s[98:99] offset:768
	s_add_u32 s98, s98, 0x1000
	s_addc_u32 s99, s99, 0
	global_load_dword v172, v182, s[98:99] offset:0
	global_load_dword v173, v182, s[98:99] offset:256
	global_load_dword v174, v182, s[98:99] offset:512
	global_load_dword v175, v182, s[98:99] offset:768
	s_add_u32 s98, s98, 0x1000
	s_addc_u32 s99, s99, 0
	global_load_dword v176, v182, s[98:99] offset:0
	global_load_dword v177, v182, s[98:99] offset:256
	global_load_dword v178, v182, s[98:99] offset:512
	global_load_dword v179, v182, s[98:99] offset:768
	v_and_b32_e32 v196, 15, v222
	v_mul_u32_u24_e32 v196, 0x1c00, v196
	v_ashrrev_i32_e32 v197, 2, v222
	v_and_b32_e32 v197, -16, v197
	v_bfe_u32 v198, v222, 4, 2
	v_lshl_or_b32 v197, v198, 2, v197
	v_lshl_add_u32 v196, v197, 1, v196
	s_lshl_b32 s99, s6, 7
	v_add_u32_e32 v196, s99, v196
	global_load_dwordx2 v[184:185], v196, s[0:1] offset:3072
	v_add_u32_e32 v198, 0x1c000, v196
	global_load_dwordx2 v[186:187], v198, s[0:1] offset:3072
	v_add_u32_e32 v198, 0x38000, v196
	global_load_dwordx2 v[188:189], v198, s[0:1] offset:3072
	v_add_u32_e32 v198, 0x54000, v196
	global_load_dwordx2 v[190:191], v198, s[0:1] offset:3072
	v_lshlrev_b32_e32 v197, 2, v197
	global_load_dwordx4 v[192:195], v197, s[34:35]
	s_waitcnt vmcnt(39)
	v_mov_b32_e32 v1, v80
	v_or_b32_e32 v2, 13, v11
	v_or_b32_e32 v43, 1, v11
	v_mad_i64_i32 v[24:25], s[8:9], v2, s48, v[4:5]
	v_or_b32_e32 v20, 15, v11
	s_movk_i32 s38, 0x500
	v_mul_lo_u32 v55, v9, s38
	v_or_b32_e32 v55, v55, v0
	v_lshl_add_u32 v55, v55, 1, 32
	s_movk_i32 s39, 0x50
	s_lshl_b32 s22, s6, 7
	s_movk_i32 s42, 0xa0
	s_lshl_b32 s5, s5, 3
	s_lshl_b32 s6, s6, 1
	s_or_b32 s5, s6, s5
	s_mulk_i32 s5, 0x44
	s_add_i32 s5, s5, s4
	s_lshl_b32 s4, s5, 12
	s_mov_b32 s5, s23
	v_bfe_u32 v10, v8, 4, 2
	s_lshl_b64 s[4:5], s[4:5], 2
	s_add_u32 s12, s2, s4
	s_addc_u32 s13, s3, s5
	v_and_b32_e32 v56, 15, v58
	v_bfe_u32 v57, v58, 4, 2
	v_mov_b32_e32 v2, v93
	s_waitcnt vmcnt(1)
	v_lshlrev_b32_e32 v47, 16, v1
	v_mov_b32_e32 v1, v96
	v_mad_i64_i32 v[6:7], s[8:9], v43, s48, v[4:5]
	v_add_f32_e32 v48, 0, v47
	v_mul_f32_e32 v59, 0x3fb8aa3b, v48
	v_exp_f32_e32 v59, v59
	v_mul_f32_e32 v47, 0x3fb8aa3b, v47
	v_exp_f32_e32 v47, v47
	s_waitcnt vmcnt(0)
	v_lshlrev_b32_e32 v46, 16, v1
	v_mov_b32_e32 v1, v81
	v_mul_f32_e32 v46, v59, v46
	v_cvt_pk_bf16_f32 v46, v46, s0
	ds_write_b16 v55, v46
	v_min_f32_e64 v46, -v48, s40
	v_mul_f32_e32 v46, 0x3fb8aa3b, v46
	v_exp_f32_e32 v46, v46
	v_sub_f32_e32 v47, 1.0, v47
	v_mul_f32_e32 v46, v47, v46
	v_cvt_pk_bf16_f32 v46, v46, s0
	ds_write_b16 v55, v46 offset:10240
	s_waitcnt vmcnt(0)
	v_lshlrev_b32_e32 v44, 16, v1
	v_mov_b32_e32 v1, v97
	v_add_f32_e32 v49, v48, v44
	v_mul_f32_e32 v44, 0x3fb8aa3b, v44
	v_exp_f32_e32 v44, v44
	s_waitcnt vmcnt(0)
	v_lshlrev_b32_e32 v42, 16, v1
	v_or_b32_e32 v1, 2, v11
	v_mad_i64_i32 v[6:7], s[8:9], v1, s48, v[4:5]
	v_mov_b32_e32 v1, v82
	v_sub_f32_e32 v44, 1.0, v44
	s_waitcnt vmcnt(0)
	v_lshlrev_b32_e32 v40, 16, v1
	v_mov_b32_e32 v1, v98
	v_add_f32_e32 v50, v49, v40
	v_mul_f32_e32 v40, 0x3fb8aa3b, v40
	v_exp_f32_e32 v40, v40
	s_waitcnt vmcnt(0)
	v_lshlrev_b32_e32 v39, 16, v1
	v_or_b32_e32 v1, 3, v11
	v_mad_i64_i32 v[6:7], s[8:9], v1, s48, v[4:5]
	v_mov_b32_e32 v1, v83
	v_sub_f32_e32 v40, 1.0, v40
	s_waitcnt vmcnt(0)
	v_lshlrev_b32_e32 v38, 16, v1
	v_mov_b32_e32 v1, v99
	v_add_f32_e32 v51, v50, v38
	v_mul_f32_e32 v38, 0x3fb8aa3b, v38
	v_exp_f32_e32 v38, v38
	s_waitcnt vmcnt(0)
	v_lshlrev_b32_e32 v36, 16, v1
	v_or_b32_e32 v1, 4, v11
	v_mad_i64_i32 v[6:7], s[8:9], v1, s48, v[4:5]
	v_mov_b32_e32 v1, v84
	v_sub_f32_e32 v38, 1.0, v38
	s_waitcnt vmcnt(0)
	v_lshlrev_b32_e32 v35, 16, v1
	v_mov_b32_e32 v1, v100
	v_add_f32_e32 v52, v51, v35
	v_mul_f32_e32 v35, 0x3fb8aa3b, v35
	v_exp_f32_e32 v35, v35
	s_waitcnt vmcnt(0)
	v_lshlrev_b32_e32 v34, 16, v1
	v_or_b32_e32 v1, 5, v11
	v_mad_i64_i32 v[6:7], s[8:9], v1, s48, v[4:5]
	v_mov_b32_e32 v1, v85
	v_sub_f32_e32 v35, 1.0, v35
	s_waitcnt vmcnt(0)
	v_lshlrev_b32_e32 v32, 16, v1
	v_mov_b32_e32 v1, v101
	v_add_f32_e32 v53, v52, v32
	v_mul_f32_e32 v32, 0x3fb8aa3b, v32
	v_exp_f32_e32 v32, v32
	s_waitcnt vmcnt(0)
	v_lshlrev_b32_e32 v31, 16, v1
	v_or_b32_e32 v1, 6, v11
	v_mad_i64_i32 v[6:7], s[8:9], v1, s48, v[4:5]
	v_mov_b32_e32 v1, v86
	v_sub_f32_e32 v32, 1.0, v32
	s_waitcnt vmcnt(0)
	v_lshlrev_b32_e32 v30, 16, v1
	v_mov_b32_e32 v1, v102
	v_add_f32_e32 v54, v53, v30
	v_mul_f32_e32 v30, 0x3fb8aa3b, v30
	v_exp_f32_e32 v30, v30
	s_waitcnt vmcnt(0)
	v_lshlrev_b32_e32 v28, 16, v1
	v_or_b32_e32 v1, 7, v11
	v_mad_i64_i32 v[6:7], s[8:9], v1, s48, v[4:5]
	v_mov_b32_e32 v1, v87
	v_sub_f32_e32 v30, 1.0, v30
	s_waitcnt vmcnt(0)
	v_lshlrev_b32_e32 v27, 16, v1
	v_mov_b32_e32 v1, v103
	v_add_f32_e32 v45, v54, v27
	v_mul_f32_e32 v27, 0x3fb8aa3b, v27
	v_exp_f32_e32 v27, v27
	s_waitcnt vmcnt(0)
	v_lshlrev_b32_e32 v26, 16, v1
	v_or_b32_e32 v1, 8, v11
	v_mad_i64_i32 v[6:7], s[8:9], v1, s48, v[4:5]
	v_mov_b32_e32 v1, v88
	v_sub_f32_e32 v27, 1.0, v27
	s_waitcnt vmcnt(0)
	v_lshlrev_b32_e32 v23, 16, v1
	v_mov_b32_e32 v1, v104
	v_add_f32_e32 v41, v45, v23
	v_mul_f32_e32 v23, 0x3fb8aa3b, v23
	v_exp_f32_e32 v23, v23
	s_waitcnt vmcnt(0)
	v_lshlrev_b32_e32 v21, 16, v1
	v_or_b32_e32 v1, 9, v11
	v_mad_i64_i32 v[6:7], s[8:9], v1, s48, v[4:5]
	v_mov_b32_e32 v1, v89
	v_sub_f32_e32 v23, 1.0, v23
	s_waitcnt vmcnt(0)
	v_lshlrev_b32_e32 v19, 16, v1
	v_mov_b32_e32 v1, v105
	v_add_f32_e32 v37, v41, v19
	v_mul_f32_e32 v19, 0x3fb8aa3b, v19
	v_exp_f32_e32 v19, v19
	s_waitcnt vmcnt(0)
	v_lshlrev_b32_e32 v18, 16, v1
	v_or_b32_e32 v1, 10, v11
	v_mad_i64_i32 v[6:7], s[8:9], v1, s48, v[4:5]
	v_mov_b32_e32 v1, v90
	v_sub_f32_e32 v19, 1.0, v19
	s_waitcnt vmcnt(0)
	v_lshlrev_b32_e32 v17, 16, v1
	v_mov_b32_e32 v1, v106
	v_add_f32_e32 v33, v37, v17
	v_mul_f32_e32 v17, 0x3fb8aa3b, v17
	v_exp_f32_e32 v17, v17
	s_waitcnt vmcnt(0)
	v_lshlrev_b32_e32 v16, 16, v1
	v_or_b32_e32 v1, 11, v11
	v_mad_i64_i32 v[6:7], s[8:9], v1, s48, v[4:5]
	v_mov_b32_e32 v1, v91
	v_sub_f32_e32 v17, 1.0, v17
	s_waitcnt vmcnt(0)
	v_lshlrev_b32_e32 v15, 16, v1
	v_mov_b32_e32 v1, v107
	v_add_f32_e32 v29, v33, v15
	v_mul_f32_e32 v15, 0x3fb8aa3b, v15
	v_exp_f32_e32 v15, v15
	s_waitcnt vmcnt(0)
	v_lshlrev_b32_e32 v14, 16, v1
	v_or_b32_e32 v1, 12, v11
	v_mad_i64_i32 v[6:7], s[8:9], v1, s48, v[4:5]
	v_mov_b32_e32 v1, v92
	v_sub_f32_e32 v15, 1.0, v15
	s_waitcnt vmcnt(0)
	v_lshlrev_b32_e32 v13, 16, v1
	v_mov_b32_e32 v1, v108
	v_or_b32_e32 v6, 14, v11
	v_lshlrev_b32_e32 v7, 16, v2
	v_mov_b32_e32 v2, v109
	v_mad_i64_i32 v[24:25], s[8:9], v6, s48, v[4:5]
	v_mov_b32_e32 v6, v94
	s_waitcnt vmcnt(2)
	v_lshlrev_b32_e32 v1, 16, v1
	s_waitcnt vmcnt(1)
	v_lshlrev_b32_e32 v2, 16, v2
	s_waitcnt vmcnt(0)
	v_lshlrev_b32_e32 v12, 16, v6
	v_mov_b32_e32 v6, v110
	v_mad_i64_i32 v[24:25], s[8:9], v20, s48, v[4:5]
	v_mov_b32_e32 v4, v95
	v_mov_b32_e32 v5, v111
	v_add_f32_e32 v25, v29, v13
	v_add_f32_e32 v24, v25, v7
	v_add_f32_e32 v22, v24, v12
	v_mul_f32_e32 v13, 0x3fb8aa3b, v13
	v_exp_f32_e32 v13, v13
	s_waitcnt vmcnt(2)
	v_lshlrev_b32_e32 v6, 16, v6
	v_sub_f32_e32 v13, 1.0, v13
	s_waitcnt vmcnt(1)
	v_lshlrev_b32_e32 v4, 16, v4
	v_add_f32_e32 v20, v22, v4
	v_sub_f32_e32 v46, v20, v48
	v_mul_f32_e32 v46, 0x3fb8aa3b, v46
	v_exp_f32_e32 v46, v46
	s_waitcnt vmcnt(0)
	v_lshlrev_b32_e32 v5, 16, v5
	v_mul_f32_e32 v46, v47, v46
	v_cvt_pk_bf16_f32 v46, v46, s0
	ds_write_b16 v55, v46 offset:20480
	v_mad_u64_u32 v[46:47], s[8:9], v43, s39, v[0:1]
	v_mul_f32_e32 v0, 0x3fb8aa3b, v49
	v_exp_f32_e32 v0, v0
	s_nop 0
	v_mul_f32_e32 v0, v0, v42
	v_cvt_pk_bf16_f32 v42, v0, s0
	v_lshl_add_u32 v0, v46, 1, 32
	ds_write_b16 v0, v42
	v_min_f32_e64 v42, -v49, s40
	v_mul_f32_e32 v42, 0x3fb8aa3b, v42
	v_exp_f32_e32 v42, v42
	s_nop 0
	v_mul_f32_e32 v42, v44, v42
	v_cvt_pk_bf16_f32 v42, v42, s0
	ds_write_b16 v0, v42 offset:10240
	v_sub_f32_e32 v42, v20, v49
	v_mul_f32_e32 v42, 0x3fb8aa3b, v42
	v_exp_f32_e32 v42, v42
	s_nop 0
	v_mul_f32_e32 v42, v44, v42
	v_cvt_pk_bf16_f32 v42, v42, s0
	ds_write_b16 v0, v42 offset:20480
	v_mul_f32_e32 v42, 0x3fb8aa3b, v50
	v_exp_f32_e32 v42, v42
	s_nop 0
	v_mul_f32_e32 v39, v42, v39
	v_cvt_pk_bf16_f32 v39, v39, s0
	ds_write_b16 v0, v39 offset:160
	v_min_f32_e64 v39, -v50, s40
	v_mul_f32_e32 v39, 0x3fb8aa3b, v39
	v_exp_f32_e32 v39, v39
	s_nop 0
	v_mul_f32_e32 v39, v40, v39
	v_cvt_pk_bf16_f32 v39, v39, s0
	ds_write_b16 v0, v39 offset:10400
	v_sub_f32_e32 v39, v20, v50
	v_mul_f32_e32 v39, 0x3fb8aa3b, v39
	v_exp_f32_e32 v39, v39
	s_nop 0
	v_mul_f32_e32 v39, v40, v39
	v_cvt_pk_bf16_f32 v39, v39, s0
	ds_write_b16 v0, v39 offset:20640
	v_mul_f32_e32 v39, 0x3fb8aa3b, v51
	v_exp_f32_e32 v39, v39
	s_nop 0
	v_mul_f32_e32 v36, v39, v36
	v_cvt_pk_bf16_f32 v36, v36, s0
	ds_write_b16 v0, v36 offset:320
	v_min_f32_e64 v36, -v51, s40
	v_mul_f32_e32 v36, 0x3fb8aa3b, v36
	v_exp_f32_e32 v36, v36
	s_nop 0
	v_mul_f32_e32 v36, v38, v36
	v_cvt_pk_bf16_f32 v36, v36, s0
	ds_write_b16 v0, v36 offset:10560
	v_sub_f32_e32 v36, v20, v51
	v_mul_f32_e32 v36, 0x3fb8aa3b, v36
	v_exp_f32_e32 v36, v36
	s_nop 0
	v_mul_f32_e32 v36, v38, v36
	v_cvt_pk_bf16_f32 v36, v36, s0
	ds_write_b16 v0, v36 offset:20800
	v_mul_f32_e32 v36, 0x3fb8aa3b, v52
	v_exp_f32_e32 v36, v36
	v_lshlrev_b32_e32 v38, 3, v10
	v_mul_f32_e32 v34, v36, v34
	v_cvt_pk_bf16_f32 v34, v34, s0
	ds_write_b16 v0, v34 offset:480
	v_min_f32_e64 v34, -v52, s40
	v_mul_f32_e32 v34, 0x3fb8aa3b, v34
	v_exp_f32_e32 v34, v34
	s_nop 0
	v_mul_f32_e32 v34, v35, v34
	v_cvt_pk_bf16_f32 v34, v34, s0
	ds_write_b16 v0, v34 offset:10720
	v_sub_f32_e32 v34, v20, v52
	v_mul_f32_e32 v34, 0x3fb8aa3b, v34
	v_exp_f32_e32 v34, v34
	s_nop 0
	v_mul_f32_e32 v34, v35, v34
	v_cvt_pk_bf16_f32 v34, v34, s0
	ds_write_b16 v0, v34 offset:20960
	v_mul_f32_e32 v34, 0x3fb8aa3b, v53
	v_exp_f32_e32 v34, v34
	s_nop 0
	v_mul_f32_e32 v31, v34, v31
	v_cvt_pk_bf16_f32 v31, v31, s0
	ds_write_b16 v0, v31 offset:640
	v_min_f32_e64 v31, -v53, s40
	v_mul_f32_e32 v31, 0x3fb8aa3b, v31
	v_exp_f32_e32 v31, v31
	s_nop 0
	v_mul_f32_e32 v31, v32, v31
	v_cvt_pk_bf16_f32 v31, v31, s0
	ds_write_b16 v0, v31 offset:10880
	v_sub_f32_e32 v31, v20, v53
	v_mul_f32_e32 v31, 0x3fb8aa3b, v31
	v_exp_f32_e32 v31, v31
	s_nop 0
	v_mul_f32_e32 v31, v32, v31
	v_cvt_pk_bf16_f32 v31, v31, s0
	ds_write_b16 v0, v31 offset:21120
	v_mul_f32_e32 v31, 0x3fb8aa3b, v54
	v_exp_f32_e32 v31, v31
	s_nop 0
	v_mul_f32_e32 v28, v31, v28
	v_cvt_pk_bf16_f32 v28, v28, s0
	ds_write_b16 v0, v28 offset:800
	v_min_f32_e64 v28, -v54, s40
	v_mul_f32_e32 v28, 0x3fb8aa3b, v28
	v_exp_f32_e32 v28, v28
	s_nop 0
	v_mul_f32_e32 v28, v30, v28
	v_cvt_pk_bf16_f32 v28, v28, s0
	ds_write_b16 v0, v28 offset:11040
	v_sub_f32_e32 v28, v20, v54
	v_mul_f32_e32 v28, 0x3fb8aa3b, v28
	v_exp_f32_e32 v28, v28
	s_nop 0
	v_mul_f32_e32 v28, v30, v28
	v_cvt_pk_bf16_f32 v28, v28, s0
	ds_write_b16 v0, v28 offset:21280
	v_mul_f32_e32 v28, 0x3fb8aa3b, v45
	v_exp_f32_e32 v28, v28
	s_nop 0
	v_mul_f32_e32 v26, v28, v26
	v_cvt_pk_bf16_f32 v26, v26, s0
	ds_write_b16 v0, v26 offset:960
	v_min_f32_e64 v26, -v45, s40
	v_mul_f32_e32 v26, 0x3fb8aa3b, v26
	v_exp_f32_e32 v26, v26
	s_nop 0
	v_mul_f32_e32 v26, v27, v26
	v_cvt_pk_bf16_f32 v26, v26, s0
	ds_write_b16 v0, v26 offset:11200
	v_sub_f32_e32 v26, v20, v45
	v_mul_f32_e32 v26, 0x3fb8aa3b, v26
	v_exp_f32_e32 v26, v26
	s_nop 0
	v_mul_f32_e32 v26, v27, v26
	v_cvt_pk_bf16_f32 v26, v26, s0
	ds_write_b16 v0, v26 offset:21440
	v_mul_f32_e32 v26, 0x3fb8aa3b, v41
	v_exp_f32_e32 v26, v26
	s_nop 0
	v_mul_f32_e32 v21, v26, v21
	v_cvt_pk_bf16_f32 v21, v21, s0
	ds_write_b16 v0, v21 offset:1120
	v_min_f32_e64 v21, -v41, s40
	v_mul_f32_e32 v21, 0x3fb8aa3b, v21
	v_exp_f32_e32 v21, v21
	s_nop 0
	v_mul_f32_e32 v21, v23, v21
	v_cvt_pk_bf16_f32 v21, v21, s0
	ds_write_b16 v0, v21 offset:11360
	v_sub_f32_e32 v21, v20, v41
	v_mul_f32_e32 v21, 0x3fb8aa3b, v21
	v_exp_f32_e32 v21, v21
	v_mov_b64_e32 v[40:41], s[0:1]
	v_mul_f32_e32 v21, v23, v21
	v_cvt_pk_bf16_f32 v21, v21, s0
	ds_write_b16 v0, v21 offset:21600
	v_mul_f32_e32 v21, 0x3fb8aa3b, v37
	v_exp_f32_e32 v21, v21
	s_nop 0
	v_mul_f32_e32 v18, v21, v18
	v_cvt_pk_bf16_f32 v18, v18, s0
	ds_write_b16 v0, v18 offset:1280
	v_min_f32_e64 v18, -v37, s40
	v_mul_f32_e32 v18, 0x3fb8aa3b, v18
	v_exp_f32_e32 v18, v18
	s_nop 0
	v_mul_f32_e32 v18, v19, v18
	v_cvt_pk_bf16_f32 v18, v18, s0
	ds_write_b16 v0, v18 offset:11520
	v_sub_f32_e32 v18, v20, v37
	v_mul_f32_e32 v18, 0x3fb8aa3b, v18
	v_exp_f32_e32 v18, v18
	v_lshl_add_u32 v37, v9, 5, 32
	v_mul_f32_e32 v18, v19, v18
	v_cvt_pk_bf16_f32 v18, v18, s0
	ds_write_b16 v0, v18 offset:21760
	v_mul_f32_e32 v18, 0x3fb8aa3b, v33
	v_exp_f32_e32 v18, v18
	s_nop 0
	v_mul_f32_e32 v16, v18, v16
	v_cvt_pk_bf16_f32 v16, v16, s0
	ds_write_b16 v0, v16 offset:1440
	v_min_f32_e64 v16, -v33, s40
	v_mul_f32_e32 v16, 0x3fb8aa3b, v16
	v_exp_f32_e32 v16, v16
	s_nop 0
	v_mul_f32_e32 v16, v17, v16
	v_cvt_pk_bf16_f32 v16, v16, s0
	ds_write_b16 v0, v16 offset:11680
	v_sub_f32_e32 v16, v20, v33
	v_mul_f32_e32 v16, 0x3fb8aa3b, v16
	v_exp_f32_e32 v16, v16
	v_lshlrev_b32_e32 v33, 2, v10
	v_mul_f32_e32 v16, v17, v16
	v_cvt_pk_bf16_f32 v16, v16, s0
	ds_write_b16 v0, v16 offset:21920
	v_mul_f32_e32 v16, 0x3fb8aa3b, v29
	v_exp_f32_e32 v16, v16
	s_nop 0
	v_mul_f32_e32 v14, v16, v14
	v_cvt_pk_bf16_f32 v14, v14, s0
	ds_write_b16 v0, v14 offset:1600
	v_min_f32_e64 v14, -v29, s40
	v_mul_f32_e32 v14, 0x3fb8aa3b, v14
	v_exp_f32_e32 v14, v14
	s_nop 0
	v_mul_f32_e32 v14, v15, v14
	v_cvt_pk_bf16_f32 v14, v14, s0
	ds_write_b16 v0, v14 offset:11840
	v_sub_f32_e32 v14, v20, v29
	v_mul_f32_e32 v14, 0x3fb8aa3b, v14
	v_exp_f32_e32 v14, v14
	s_nop 0
	v_mul_f32_e32 v14, v15, v14
	v_cvt_pk_bf16_f32 v14, v14, s0
	ds_write_b16 v0, v14 offset:22080
	v_mul_f32_e32 v14, 0x3fb8aa3b, v25
	v_exp_f32_e32 v14, v14
	s_nop 0
	v_mul_f32_e32 v1, v14, v1
	v_cvt_pk_bf16_f32 v1, v1, s0
	ds_write_b16 v0, v1 offset:1760
	v_min_f32_e64 v1, -v25, s40
	v_mul_f32_e32 v1, 0x3fb8aa3b, v1
	v_exp_f32_e32 v1, v1
	s_nop 0
	v_mul_f32_e32 v1, v13, v1
	v_cvt_pk_bf16_f32 v1, v1, s0
	ds_write_b16 v0, v1 offset:12000
	v_sub_f32_e32 v1, v20, v25
	v_mul_f32_e32 v1, 0x3fb8aa3b, v1
	v_exp_f32_e32 v1, v1
	s_nop 0
	v_mul_f32_e32 v1, v13, v1
	v_cvt_pk_bf16_f32 v1, v1, s0
	ds_write_b16 v0, v1 offset:22240
	v_mul_f32_e32 v1, 0x3fb8aa3b, v7
	v_mul_f32_e32 v7, 0x3fb8aa3b, v24
	v_exp_f32_e32 v7, v7
	v_exp_f32_e32 v1, v1
	v_mul_f32_e32 v2, v7, v2
	v_cvt_pk_bf16_f32 v2, v2, s0
	ds_write_b16 v0, v2 offset:1920
	v_min_f32_e64 v2, -v24, s40
	v_mul_f32_e32 v2, 0x3fb8aa3b, v2
	v_exp_f32_e32 v2, v2
	v_sub_f32_e32 v1, 1.0, v1
	v_mul_f32_e32 v2, v1, v2
	v_cvt_pk_bf16_f32 v2, v2, s0
	ds_write_b16 v0, v2 offset:12160
	v_sub_f32_e32 v2, v20, v24
	v_mul_f32_e32 v2, 0x3fb8aa3b, v2
	v_exp_f32_e32 v2, v2
	s_nop 0
	v_mul_f32_e32 v1, v1, v2
	v_mul_f32_e32 v2, 0x3fb8aa3b, v22
	v_exp_f32_e32 v2, v2
	v_cvt_pk_bf16_f32 v1, v1, s0
	ds_write_b16 v0, v1 offset:22400
	v_mul_f32_e32 v1, 0x3fb8aa3b, v12
	v_mul_f32_e32 v2, v2, v6
	v_cvt_pk_bf16_f32 v2, v2, s0
	ds_write_b16 v0, v2 offset:2080
	v_min_f32_e64 v2, -v22, s40
	v_exp_f32_e32 v1, v1
	v_mul_f32_e32 v2, 0x3fb8aa3b, v2
	v_exp_f32_e32 v2, v2
	v_lshlrev_b32_e32 v12, 2, v8
	v_sub_f32_e32 v1, 1.0, v1
	v_and_b32_e32 v35, 12, v12
	v_mul_f32_e32 v2, v1, v2
	v_cvt_pk_bf16_f32 v2, v2, s0
	ds_write_b16 v0, v2 offset:12320
	v_sub_f32_e32 v2, v20, v22
	v_mul_f32_e32 v2, 0x3fb8aa3b, v2
	v_exp_f32_e32 v2, v2
	s_nop 0
	v_mul_f32_e32 v1, v1, v2
	v_mul_f32_e32 v2, 0x3fb8aa3b, v20
	v_exp_f32_e32 v2, v2
	v_cvt_pk_bf16_f32 v1, v1, s0
	ds_write_b16 v0, v1 offset:22560
	v_mul_f32_e32 v1, 0x3fb8aa3b, v4
	v_mul_f32_e32 v4, v2, v5
	v_cvt_pk_bf16_f32 v4, v4, s0
	ds_write_b16 v0, v4 offset:2240
	v_min_f32_e64 v4, -v20, s40
	v_exp_f32_e32 v1, v1
	v_mul_f32_e32 v4, 0x3fb8aa3b, v4
	v_exp_f32_e32 v4, v4
	v_sub_f32_e32 v1, 1.0, v1
	v_mul_f32_e32 v4, v1, v4
	v_cvt_pk_bf16_f32 v4, v4, s0
	ds_write_b16 v0, v4 offset:12480
	v_sub_f32_e32 v4, v20, v20
	v_mul_f32_e32 v4, 0x3fb8aa3b, v4
	v_exp_f32_e32 v4, v4
	s_nop 0
	v_mul_f32_e32 v1, v1, v4
	v_cvt_pk_bf16_f32 v1, v1, s0
	ds_write_b16 v0, v1 offset:22720
	v_add_u32_e32 v0, 32, v12
	v_ashrrev_i32_e32 v1, 3, v8
	ds_write_b32 v0, v2 offset:40960
	v_lshlrev_b32_e32 v0, 4, v8
	v_mad_i64_i32 v[4:5], s[8:9], v1, s48, v[40:41]
	v_and_b32_e32 v2, 0x70, v0
	v_lshl_add_u64 v[4:5], v[4:5], 0, s[22:23]
	v_lshl_add_u64 v[4:5], v[4:5], 0, v[2:3]
	s_waitcnt vmcnt(37)
	v_mov_b32_e32 v4, v140
	v_mov_b32_e32 v5, v141
	v_mov_b32_e32 v6, v142
	v_mov_b32_e32 v7, v143
	v_add_u32_e32 v0, 32, v2
	v_mad_u64_u32 v[14:15], s[8:9], v1, s42, v[0:1]
	v_add_u32_e32 v1, 0x100, v8
	v_ashrrev_i32_e32 v1, 3, v1
	s_waitcnt vmcnt(0)
	ds_write_b128 v14, v[4:7] offset:30720
	v_mad_i64_i32 v[4:5], s[8:9], v1, s48, v[40:41]
	v_lshl_add_u64 v[4:5], v[4:5], 0, s[22:23]
	v_lshl_add_u64 v[4:5], v[4:5], 0, v[2:3]
	v_mov_b32_e32 v4, v144
	v_mov_b32_e32 v5, v145
	v_mov_b32_e32 v6, v146
	v_mov_b32_e32 v7, v147
	v_mad_u64_u32 v[0:1], s[8:9], v1, s42, v[0:1]
	v_and_b32_e32 v2, 15, v8
	v_cmp_gt_u32_e32 vcc, v33, v2
	v_cmp_lt_u32_e64 s[4:5], v33, v2
	s_waitcnt vmcnt(0)
	ds_write_b128 v0, v[4:7] offset:30720
	v_or_b32_e32 v0, v11, v2
	v_lshl_add_u32 v0, v10, 8, v0
	v_ashrrev_i32_e32 v1, 31, v0
	v_lshl_add_u64 v[4:5], v[0:1], 2, s[12:13]
	s_waitcnt lgkmcnt(0)
	s_barrier
	s_waitcnt vmcnt(21)
	v_mov_b32_e32 v16, v148
	v_mov_b32_e32 v17, v149
	v_mov_b32_e32 v18, v150
	v_mov_b32_e32 v19, v151
	v_add_u32_e32 v4, 0x400, v0
	v_ashrrev_i32_e32 v5, 31, v4
	v_lshl_add_u64 v[4:5], v[4:5], 2, s[12:13]
	v_mov_b32_e32 v20, v152
	v_add_u32_e32 v4, 0x440, v0
	v_ashrrev_i32_e32 v5, 31, v4
	v_lshl_add_u64 v[4:5], v[4:5], 2, s[12:13]
	v_mov_b32_e32 v21, v153
	v_add_u32_e32 v4, 0x480, v0
	v_ashrrev_i32_e32 v5, 31, v4
	v_lshl_add_u64 v[4:5], v[4:5], 2, s[12:13]
	v_mov_b32_e32 v22, v154
	v_add_u32_e32 v4, 0x4c0, v0
	v_ashrrev_i32_e32 v5, 31, v4
	v_lshl_add_u64 v[4:5], v[4:5], 2, s[12:13]
	v_mov_b32_e32 v23, v155
	v_add_u32_e32 v4, 0x800, v0
	v_ashrrev_i32_e32 v5, 31, v4
	v_lshl_add_u64 v[4:5], v[4:5], 2, s[12:13]
	v_mov_b32_e32 v24, v156
	v_add_u32_e32 v4, 0x840, v0
	v_ashrrev_i32_e32 v5, 31, v4
	v_lshl_add_u64 v[4:5], v[4:5], 2, s[12:13]
	v_mov_b32_e32 v25, v157
	v_add_u32_e32 v4, 0x880, v0
	v_ashrrev_i32_e32 v5, 31, v4
	v_lshl_add_u64 v[4:5], v[4:5], 2, s[12:13]
	v_mov_b32_e32 v26, v158
	v_add_u32_e32 v4, 0x8c0, v0
	v_ashrrev_i32_e32 v5, 31, v4
	v_lshl_add_u64 v[4:5], v[4:5], 2, s[12:13]
	v_mov_b32_e32 v27, v159
	v_add_u32_e32 v4, 0xc00, v0
	v_ashrrev_i32_e32 v5, 31, v4
	v_lshl_add_u64 v[4:5], v[4:5], 2, s[12:13]
	v_mov_b32_e32 v28, v160
	v_add_u32_e32 v4, 0xc40, v0
	v_ashrrev_i32_e32 v5, 31, v4
	v_lshl_add_u64 v[4:5], v[4:5], 2, s[12:13]
	v_mov_b32_e32 v29, v161
	v_add_u32_e32 v4, 0xc80, v0
	v_add_u32_e32 v0, 0xcc0, v0
	v_ashrrev_i32_e32 v5, 31, v4
	v_ashrrev_i32_e32 v1, 31, v0
	v_lshl_add_u64 v[4:5], v[4:5], 2, s[12:13]
	v_lshl_add_u64 v[0:1], v[0:1], 2, s[12:13]
	v_mov_b32_e32 v30, v162
	v_mov_b32_e32 v31, v163
	v_bfe_u32 v0, v8, 2, 2
	v_and_b32_e32 v8, 48, v8
	v_mul_u32_u24_e32 v4, 0x50, v2
	v_add_u32_e32 v39, 32, v8
	v_lshlrev_b32_e32 v9, 1, v4
	v_add_u32_e32 v32, v39, v9
	ds_read_b128 v[4:7], v32 offset:10240
	v_add3_u32 v36, 32, v9, v8
	v_or_b32_e32 v34, v33, v0
	ds_read_b128 v[8:11], v36
	v_mul_u32_u24_e32 v0, 0x50, v34
	v_or_b32_e32 v0, v0, v35
	v_lshlrev_b32_e32 v43, 1, v0
	v_add_u32_e32 v44, v37, v43
	ds_read_b64_tr_b16 v[0:1], v44 offset:30720
	s_waitcnt lgkmcnt(1)
	v_mfma_f32_16x16x32_bf16 v[4:7], v[4:7], v[8:11], 0
	ds_read_b128 v[8:11], v32 offset:10304
	ds_read_b128 v[12:15], v36 offset:64
	v_sub_u32_e32 v42, v36, v38
	v_add_u32_e32 v38, 0x800, v42
	s_waitcnt lgkmcnt(0)
	v_mfma_f32_16x16x32_bf16 v[4:7], v[8:11], v[12:15], v[4:7]
	v_or_b32_e32 v8, 2, v33
	v_cmp_gt_u32_e64 s[6:7], v8, v2
	v_or_b32_e32 v8, 3, v33
	v_cmp_gt_u32_e64 s[8:9], v8, v2
	s_nop 3
	v_cndmask_b32_e64 v4, v4, 0, vcc
	v_cndmask_b32_e64 v5, 0, v5, s[4:5]
	v_cndmask_b32_e64 v6, v6, 0, s[6:7]
	v_cndmask_b32_e64 v2, v7, 0, s[8:9]
	v_cvt_pk_bf16_f32 v4, v4, v5
	v_cvt_pk_bf16_f32 v5, v6, v2
	v_mov_b32_e32 v2, v3
	v_mov_b32_e32 v6, v3
	v_mov_b32_e32 v7, v3
	s_waitcnt vmcnt(14)
	v_cvt_pk_bf16_f32 v8, v16, v17
	s_waitcnt vmcnt(12)
	v_cvt_pk_bf16_f32 v9, v18, v19
	ds_read2_b64 v[12:15], v42 offset1:4
	v_mfma_f32_16x16x32_bf16 v[4:7], v[0:3], v[4:7], 0
	s_waitcnt vmcnt(10)
	v_cvt_pk_bf16_f32 v10, v20, v21
	v_add_u32_e32 v33, 32, v43
	s_waitcnt vmcnt(8)
	v_cvt_pk_bf16_f32 v11, v22, v23
	s_waitcnt lgkmcnt(0)
	s_nop 0
	v_mfma_f32_16x16x32_bf16 v[4:7], v[8:11], v[12:15], v[4:7]
	ds_read2_b64 v[12:15], v42 offset0:8 offset1:12
	s_waitcnt vmcnt(6)
	v_cvt_pk_bf16_f32 v8, v24, v25
	s_waitcnt vmcnt(4)
	v_cvt_pk_bf16_f32 v9, v26, v27
	s_waitcnt vmcnt(2)
	v_cvt_pk_bf16_f32 v10, v28, v29
	s_waitcnt vmcnt(0)
	v_cvt_pk_bf16_f32 v11, v30, v31
	s_waitcnt lgkmcnt(0)
	s_nop 0
	v_mfma_f32_16x16x32_bf16 v[4:7], v[8:11], v[12:15], v[4:7]
	v_mov_b32_e32 v10, v3
	v_mov_b32_e32 v11, v3
	v_mov_b32_e32 v14, v3
	s_nop 4
	v_pk_add_f32 v[52:53], v[6:7], 0 op_sel_hi:[1,0]
	v_pk_add_f32 v[54:55], v[4:5], 0 op_sel_hi:[1,0]
	ds_read_b128 v[4:7], v39 offset:40960
	ds_read_b64_tr_b16 v[8:9], v33 offset:20480
	ds_read_b64_tr_b16 v[12:13], v33 offset:20512
	v_mov_b32_e32 v15, v3
	s_waitcnt lgkmcnt(2)
	v_pk_mul_f32 v[4:5], v[16:17], v[4:5]
	v_pk_mul_f32 v[6:7], v[18:19], v[6:7]
	ds_read_b64_tr_b16 v[16:17], v33 offset:20544
	v_mov_b32_e32 v18, v3
	s_waitcnt lgkmcnt(2)
	v_mfma_f32_16x16x32_bf16 v[8:11], v[8:11], v[0:3], v[4:7]
	v_mov_b32_e32 v19, v3
	s_nop 1
	ds_read_b128 v[4:7], v39 offset:41024
	s_waitcnt lgkmcnt(0)
	v_pk_mul_f32 v[4:5], v[20:21], v[4:5]
	v_pk_mul_f32 v[6:7], v[22:23], v[6:7]
	ds_read_b64_tr_b16 v[20:21], v33 offset:20576
	v_mov_b32_e32 v22, v3
	v_mfma_f32_16x16x32_bf16 v[12:15], v[12:15], v[0:3], v[4:7]
	v_mov_b32_e32 v23, v3
	s_nop 1
	ds_read_b128 v[4:7], v39 offset:41088
	s_waitcnt lgkmcnt(0)
	v_pk_mul_f32 v[4:5], v[24:25], v[4:5]
	v_pk_mul_f32 v[6:7], v[26:27], v[6:7]
	s_nop 1
	v_mfma_f32_16x16x32_bf16 v[16:19], v[16:19], v[0:3], v[4:7]
	s_nop 2
	ds_read_b128 v[4:7], v39 offset:41152
	s_waitcnt lgkmcnt(0)
	v_pk_mul_f32 v[4:5], v[28:29], v[4:5]
	v_pk_mul_f32 v[6:7], v[30:31], v[6:7]
	s_nop 1
	v_mfma_f32_16x16x32_bf16 v[20:23], v[20:23], v[0:3], v[4:7]
	ds_read_b64_tr_b16 v[0:1], v44 offset:33280
	s_nop 1
	ds_read_b128 v[4:7], v32 offset:12800
	ds_read_b128 v[24:27], v36 offset:2560
	s_waitcnt lgkmcnt(0)
	v_mfma_f32_16x16x32_bf16 v[4:7], v[4:7], v[24:27], 0
	ds_read_b128 v[24:27], v32 offset:12864
	ds_read_b128 v[28:31], v36 offset:2624
	s_waitcnt lgkmcnt(0)
	v_mfma_f32_16x16x32_bf16 v[4:7], v[24:27], v[28:31], v[4:7]
	v_cvt_pk_bf16_f32 v24, v8, v9
	v_cvt_pk_bf16_f32 v25, v10, v11
	v_cvt_pk_bf16_f32 v26, v12, v13
	s_nop 4
	v_cndmask_b32_e64 v2, v4, 0, vcc
	v_cndmask_b32_e64 v4, 0, v5, s[4:5]
	v_cvt_pk_bf16_f32 v4, v2, v4
	v_mov_b32_e32 v2, v3
	v_cndmask_b32_e64 v5, v6, 0, s[6:7]
	v_cndmask_b32_e64 v6, v7, 0, s[8:9]
	v_cvt_pk_bf16_f32 v5, v5, v6
	v_mov_b32_e32 v6, v3
	v_mov_b32_e32 v7, v3
	v_cvt_pk_bf16_f32 v27, v14, v15
	ds_read2_b64 v[28:31], v38 offset0:64 offset1:68
	v_mfma_f32_16x16x32_bf16 v[4:7], v[0:3], v[4:7], 0
	s_waitcnt lgkmcnt(0)
	v_mfma_f32_16x16x32_bf16 v[4:7], v[24:27], v[28:31], v[4:7]
	v_cvt_pk_bf16_f32 v24, v16, v17
	v_cvt_pk_bf16_f32 v25, v18, v19
	v_cvt_pk_bf16_f32 v26, v20, v21
	v_cvt_pk_bf16_f32 v27, v22, v23
	ds_read2_b64 v[28:31], v38 offset0:72 offset1:76
	v_add_u32_e32 v38, 0x1000, v42
	s_waitcnt lgkmcnt(0)
	v_mfma_f32_16x16x32_bf16 v[4:7], v[24:27], v[28:31], v[4:7]
	ds_read_b128 v[24:27], v39 offset:41216
	s_waitcnt lgkmcnt(0)
	v_pk_mul_f32 v[8:9], v[8:9], v[24:25]
	ds_read_b64_tr_b16 v[24:25], v33 offset:23040
	v_pk_mul_f32 v[10:11], v[10:11], v[26:27]
	v_mov_b32_e32 v26, v3
	v_mov_b32_e32 v27, v3
	s_waitcnt lgkmcnt(0)
	s_nop 0
	v_mfma_f32_16x16x32_bf16 v[24:27], v[24:27], v[0:3], v[8:11]
	s_nop 2
	ds_read_b128 v[8:11], v39 offset:41280
	s_waitcnt lgkmcnt(0)
	v_pk_mul_f32 v[8:9], v[12:13], v[8:9]
	ds_read_b64_tr_b16 v[12:13], v33 offset:23072
	v_pk_mul_f32 v[10:11], v[14:15], v[10:11]
	v_mov_b32_e32 v14, v3
	v_mov_b32_e32 v15, v3
	s_waitcnt lgkmcnt(0)
	s_nop 0
	v_mfma_f32_16x16x32_bf16 v[12:15], v[12:15], v[0:3], v[8:11]
	s_nop 2
	ds_read_b128 v[8:11], v39 offset:41344
	s_waitcnt lgkmcnt(0)
	v_pk_mul_f32 v[8:9], v[16:17], v[8:9]
	ds_read_b64_tr_b16 v[16:17], v33 offset:23104
	v_pk_mul_f32 v[10:11], v[18:19], v[10:11]
	v_mov_b32_e32 v18, v3
	v_mov_b32_e32 v19, v3
	s_waitcnt lgkmcnt(0)
	s_nop 0
	v_mfma_f32_16x16x32_bf16 v[16:19], v[16:19], v[0:3], v[8:11]
	s_nop 2
	ds_read_b128 v[8:11], v39 offset:41408
	s_waitcnt lgkmcnt(0)
	v_pk_mul_f32 v[8:9], v[20:21], v[8:9]
	ds_read_b64_tr_b16 v[20:21], v33 offset:23136
	v_pk_mul_f32 v[10:11], v[22:23], v[10:11]
	v_mov_b32_e32 v22, v3
	v_mov_b32_e32 v23, v3
	s_waitcnt lgkmcnt(0)
	s_nop 0
	v_mfma_f32_16x16x32_bf16 v[28:31], v[20:23], v[0:3], v[8:11]
	ds_read_b64_tr_b16 v[0:1], v44 offset:35840
	s_nop 1
	ds_read_b128 v[8:11], v32 offset:15360
	ds_read_b128 v[20:23], v36 offset:5120
	s_waitcnt lgkmcnt(0)
	v_mfma_f32_16x16x32_bf16 v[8:11], v[8:11], v[20:23], 0
	ds_read_b128 v[20:23], v32 offset:15424
	ds_read_b128 v[44:47], v36 offset:5184
	s_waitcnt lgkmcnt(0)
	v_mfma_f32_16x16x32_bf16 v[8:11], v[20:23], v[44:47], v[8:11]
	v_cvt_pk_bf16_f32 v20, v24, v25
	v_cvt_pk_bf16_f32 v21, v26, v27
	v_cvt_pk_bf16_f32 v22, v12, v13
	s_nop 4
	v_cndmask_b32_e64 v2, v8, 0, vcc
	v_cndmask_b32_e64 v8, 0, v9, s[4:5]
	v_cvt_pk_bf16_f32 v8, v2, v8
	v_mov_b32_e32 v2, v3
	v_cndmask_b32_e64 v9, v10, 0, s[6:7]
	v_cndmask_b32_e64 v10, v11, 0, s[8:9]
	v_cvt_pk_bf16_f32 v9, v9, v10
	v_mov_b32_e32 v10, v3
	v_mov_b32_e32 v11, v3
	v_cvt_pk_bf16_f32 v23, v14, v15
	ds_read2_b64 v[44:47], v38 offset0:128 offset1:132
	v_mfma_f32_16x16x32_bf16 v[8:11], v[0:3], v[8:11], 0
	s_waitcnt lgkmcnt(0)
	v_mfma_f32_16x16x32_bf16 v[8:11], v[20:23], v[44:47], v[8:11]
	v_cvt_pk_bf16_f32 v20, v16, v17
	v_cvt_pk_bf16_f32 v21, v18, v19
	v_cvt_pk_bf16_f32 v22, v28, v29
	v_cvt_pk_bf16_f32 v23, v30, v31
	ds_read2_b64 v[44:47], v38 offset0:136 offset1:140
	s_waitcnt lgkmcnt(0)
	v_mfma_f32_16x16x32_bf16 v[8:11], v[20:23], v[44:47], v[8:11]
	ds_read_b128 v[20:23], v39 offset:41472
	s_waitcnt lgkmcnt(0)
	v_pk_mul_f32 v[20:21], v[24:25], v[20:21]
	ds_read_b64_tr_b16 v[24:25], v33 offset:25600
	v_pk_mul_f32 v[22:23], v[26:27], v[22:23]
	v_mov_b32_e32 v26, v3
	v_mov_b32_e32 v27, v3
	s_waitcnt lgkmcnt(0)
	s_nop 0
	v_mfma_f32_16x16x32_bf16 v[20:23], v[24:27], v[0:3], v[20:23]
	ds_read_b128 v[24:27], v39 offset:41536
	s_waitcnt lgkmcnt(0)
	v_pk_mul_f32 v[12:13], v[12:13], v[24:25]
	ds_read_b64_tr_b16 v[24:25], v33 offset:25632
	v_pk_mul_f32 v[14:15], v[14:15], v[26:27]
	v_mov_b32_e32 v26, v3
	v_mov_b32_e32 v27, v3
	s_nop 0
	v_cvt_pk_bf16_f32 v20, v20, v21
	v_cvt_pk_bf16_f32 v21, v22, v23
	s_waitcnt lgkmcnt(0)
	v_mfma_f32_16x16x32_bf16 v[24:27], v[24:27], v[0:3], v[12:15]
	s_nop 2
	ds_read_b128 v[12:15], v39 offset:41600
	s_waitcnt lgkmcnt(0)
	v_pk_mul_f32 v[12:13], v[16:17], v[12:13]
	ds_read_b64_tr_b16 v[16:17], v33 offset:25664
	v_pk_mul_f32 v[14:15], v[18:19], v[14:15]
	v_mov_b32_e32 v18, v3
	v_mov_b32_e32 v19, v3
	v_cvt_pk_bf16_f32 v22, v24, v25
	v_cvt_pk_bf16_f32 v23, v26, v27
	s_waitcnt lgkmcnt(0)
	v_mfma_f32_16x16x32_bf16 v[12:15], v[16:19], v[0:3], v[12:15]
	ds_read_b128 v[16:19], v39 offset:41664
	s_waitcnt lgkmcnt(0)
	v_pk_mul_f32 v[16:17], v[28:29], v[16:17]
	ds_read_b64_tr_b16 v[28:29], v33 offset:25696
	v_pk_mul_f32 v[18:19], v[30:31], v[18:19]
	v_mov_b32_e32 v30, v3
	v_mov_b32_e32 v31, v3
	s_nop 0
	v_cvt_pk_bf16_f32 v12, v12, v13
	v_cvt_pk_bf16_f32 v13, v14, v15
	s_waitcnt lgkmcnt(0)
	v_mfma_f32_16x16x32_bf16 v[16:19], v[28:31], v[0:3], v[16:19]
	v_mul_u32_u24_e32 v0, 0xa0, v34
	v_lshlrev_b32_e32 v1, 1, v35
	v_add3_u32 v0, v37, v0, v1
	ds_read_b64_tr_b16 v[0:1], v0 offset:38400
	ds_read_b128 v[28:31], v32 offset:17920
	ds_read_b128 v[44:47], v36 offset:7680
	ds_read_b128 v[32:35], v32 offset:17984
	ds_read_b128 v[36:39], v36 offset:7744
	s_waitcnt lgkmcnt(2)
	v_mfma_f32_16x16x32_bf16 v[28:31], v[28:31], v[44:47], 0
	v_cvt_pk_bf16_f32 v14, v16, v17
	v_cvt_pk_bf16_f32 v15, v18, v19
	s_waitcnt lgkmcnt(0)
	v_mfma_f32_16x16x32_bf16 v[28:31], v[32:35], v[36:39], v[28:31]
	s_nop 7
	v_cndmask_b32_e64 v2, v28, 0, vcc
	v_cndmask_b32_e64 v28, 0, v29, s[4:5]
	v_cvt_pk_bf16_f32 v28, v2, v28
	v_mov_b32_e32 v2, v3
	v_cndmask_b32_e64 v29, v30, 0, s[6:7]
	v_cndmask_b32_e64 v30, v31, 0, s[8:9]
	v_cvt_pk_bf16_f32 v29, v29, v30
	v_mov_b32_e32 v30, v3
	v_mov_b32_e32 v31, v3
	s_nop 1
	v_mfma_f32_16x16x32_bf16 v[28:31], v[0:3], v[28:31], 0
	v_add_u32_e32 v0, 0x1800, v42
	ds_read2_b64 v[24:27], v0 offset0:192 offset1:196
	ds_read2_b64 v[16:19], v0 offset0:200 offset1:204
	s_waitcnt lgkmcnt(1)
	v_mfma_f32_16x16x32_bf16 v[20:23], v[20:23], v[24:27], v[28:31]
	v_mov_b32_e32 v24, v222
	s_waitcnt lgkmcnt(0)
	v_and_b32_e32 v0, 63, v24
	v_or_b32_e32 v1, s33, v0
	v_ashrrev_i32_e32 v25, 6, v24
	v_lshlrev_b32_e32 v2, 1, v1
	v_mfma_f32_16x16x32_bf16 v[12:15], v[12:15], v[16:19], v[20:23]
	v_lshl_add_u64 v[16:17], s[0:1], 0, v[2:3]
	s_barrier
	s_nop 0
	v_lshlrev_b32_e32 v20, 4, v25
	v_mad_i64_i32 v[18:19], s[4:5], v20, s48, v[16:17]
	v_mov_b32_e32 v1, v112
	v_or_b32_e32 v2, 13, v20
	v_or_b32_e32 v64, 1, v20
	v_mad_i64_i32 v[38:39], s[4:5], v2, s48, v[16:17]
	v_mov_b32_e32 v2, v125
	v_or_b32_e32 v37, 15, v20
	v_bfe_u32 v26, v24, 4, 2
	s_waitcnt vmcnt(1)
	v_lshlrev_b32_e32 v43, 16, v1
	v_mov_b32_e32 v1, v96
	v_mad_i64_i32 v[18:19], s[4:5], v64, s48, v[16:17]
	s_waitcnt vmcnt(0)
	v_lshlrev_b32_e32 v67, 16, v1
	v_mov_b32_e32 v1, v113
	s_waitcnt vmcnt(0)
	v_lshlrev_b32_e32 v66, 16, v1
	v_mov_b32_e32 v1, v97
	s_waitcnt vmcnt(0)
	v_lshlrev_b32_e32 v63, 16, v1
	v_or_b32_e32 v1, 2, v20
	v_mad_i64_i32 v[18:19], s[4:5], v1, s48, v[16:17]
	v_mov_b32_e32 v1, v114
	s_waitcnt vmcnt(0)
	v_lshlrev_b32_e32 v62, 16, v1
	v_mov_b32_e32 v1, v98
	s_waitcnt vmcnt(0)
	v_lshlrev_b32_e32 v60, 16, v1
	v_or_b32_e32 v1, 3, v20
	v_mad_i64_i32 v[18:19], s[4:5], v1, s48, v[16:17]
	v_mov_b32_e32 v1, v115
	s_waitcnt vmcnt(0)
	v_lshlrev_b32_e32 v59, 16, v1
	v_mov_b32_e32 v1, v99
	s_waitcnt vmcnt(0)
	v_lshlrev_b32_e32 v51, 16, v1
	v_or_b32_e32 v1, 4, v20
	v_mad_i64_i32 v[18:19], s[4:5], v1, s48, v[16:17]
	v_mov_b32_e32 v1, v116
	s_waitcnt vmcnt(0)
	v_lshlrev_b32_e32 v49, 16, v1
	v_mov_b32_e32 v1, v100
	s_waitcnt vmcnt(0)
	v_lshlrev_b32_e32 v48, 16, v1
	v_or_b32_e32 v1, 5, v20
	v_mad_i64_i32 v[18:19], s[4:5], v1, s48, v[16:17]
	v_mov_b32_e32 v1, v117
	s_waitcnt vmcnt(0)
	v_lshlrev_b32_e32 v47, 16, v1
	v_mov_b32_e32 v1, v101
	s_waitcnt vmcnt(0)
	v_lshlrev_b32_e32 v45, 16, v1
	v_or_b32_e32 v1, 6, v20
	v_mad_i64_i32 v[18:19], s[4:5], v1, s48, v[16:17]
	v_mov_b32_e32 v1, v118
	s_waitcnt vmcnt(0)
	v_lshlrev_b32_e32 v42, 16, v1
	v_mov_b32_e32 v1, v102
	s_waitcnt vmcnt(0)
	v_lshlrev_b32_e32 v36, 16, v1
	v_or_b32_e32 v1, 7, v20
	v_mad_i64_i32 v[18:19], s[4:5], v1, s48, v[16:17]
	v_mov_b32_e32 v1, v119
	s_waitcnt vmcnt(0)
	v_lshlrev_b32_e32 v35, 16, v1
	v_mov_b32_e32 v1, v103
	s_waitcnt vmcnt(0)
	v_lshlrev_b32_e32 v34, 16, v1
	v_or_b32_e32 v1, 8, v20
	v_mad_i64_i32 v[18:19], s[4:5], v1, s48, v[16:17]
	v_mov_b32_e32 v1, v120
	s_waitcnt vmcnt(0)
	v_lshlrev_b32_e32 v33, 16, v1
	v_mov_b32_e32 v1, v104
	s_waitcnt vmcnt(0)
	v_lshlrev_b32_e32 v32, 16, v1
	v_or_b32_e32 v1, 9, v20
	v_mad_i64_i32 v[18:19], s[4:5], v1, s48, v[16:17]
	v_mov_b32_e32 v1, v121
	s_waitcnt vmcnt(0)
	v_lshlrev_b32_e32 v31, 16, v1
	v_mov_b32_e32 v1, v105
	s_waitcnt vmcnt(0)
	v_lshlrev_b32_e32 v30, 16, v1
	v_or_b32_e32 v1, 10, v20
	v_mad_i64_i32 v[18:19], s[4:5], v1, s48, v[16:17]
	v_mov_b32_e32 v1, v122
	s_waitcnt vmcnt(0)
	v_lshlrev_b32_e32 v29, 16, v1
	v_mov_b32_e32 v1, v106
	s_waitcnt vmcnt(0)
	v_lshlrev_b32_e32 v28, 16, v1
	v_or_b32_e32 v1, 11, v20
	v_mad_i64_i32 v[18:19], s[4:5], v1, s48, v[16:17]
	v_mov_b32_e32 v1, v123
	s_waitcnt vmcnt(0)
	v_lshlrev_b32_e32 v27, 16, v1
	v_mov_b32_e32 v1, v107
	s_waitcnt vmcnt(0)
	v_lshlrev_b32_e32 v23, 16, v1
	v_or_b32_e32 v1, 12, v20
	v_mad_i64_i32 v[18:19], s[4:5], v1, s48, v[16:17]
	v_mov_b32_e32 v1, v124
	s_waitcnt vmcnt(0)
	v_lshlrev_b32_e32 v22, 16, v1
	v_mov_b32_e32 v1, v108
	v_or_b32_e32 v18, 14, v20
	v_lshlrev_b32_e32 v19, 16, v2
	v_mov_b32_e32 v2, v109
	v_mad_i64_i32 v[38:39], s[4:5], v18, s48, v[16:17]
	v_mov_b32_e32 v18, v126
	s_waitcnt vmcnt(2)
	v_lshlrev_b32_e32 v1, 16, v1
	s_waitcnt vmcnt(1)
	v_lshlrev_b32_e32 v2, 16, v2
	s_waitcnt vmcnt(0)
	v_lshlrev_b32_e32 v21, 16, v18
	v_mov_b32_e32 v18, v110
	v_mad_i64_i32 v[38:39], s[4:5], v37, s48, v[16:17]
	v_mov_b32_e32 v16, v127
	v_mov_b32_e32 v17, v111
	s_waitcnt vmcnt(2)
	v_lshlrev_b32_e32 v18, 16, v18
	s_waitcnt vmcnt(1)
	v_lshlrev_b32_e32 v16, 16, v16
	s_waitcnt vmcnt(0)
	v_lshlrev_b32_e32 v37, 16, v17
	v_add_f32_e32 v17, 0, v16
	v_add_f32_e32 v39, v17, v21
	v_add_f32_e32 v44, v39, v19
	v_add_f32_e32 v46, v44, v22
	v_add_f32_e32 v50, v46, v27
	v_add_f32_e32 v61, v50, v29
	v_add_f32_e32 v65, v61, v31
	v_add_f32_e32 v68, v65, v33
	v_add_f32_e32 v69, v68, v35
	v_add_f32_e32 v70, v69, v42
	v_add_f32_e32 v71, v70, v47
	v_add_f32_e32 v72, v71, v49
	v_add_f32_e32 v73, v72, v59
	v_add_f32_e32 v74, v73, v62
	v_add_f32_e32 v75, v74, v66
	v_add_f32_e32 v38, v75, v43
	v_mul_f32_e32 v43, 0x3fb8aa3b, v43
	v_exp_f32_e32 v43, v43
	v_mul_f32_e32 v66, 0x3fb8aa3b, v66
	v_exp_f32_e32 v66, v66
	v_mul_f32_e32 v62, 0x3fb8aa3b, v62
	v_sub_f32_e32 v76, 1.0, v43
	v_mul_lo_u32 v43, v25, s38
	v_or_b32_e32 v77, v43, v0
	v_mul_f32_e32 v43, 0x3fb8aa3b, v38
	v_exp_f32_e32 v43, v43
	v_lshl_add_u32 v77, v77, 1, 32
	v_exp_f32_e32 v62, v62
	v_mul_f32_e32 v59, 0x3fb8aa3b, v59
	v_mul_f32_e32 v67, v43, v67
	v_cvt_pk_bf16_f32 v67, v67, s0
	ds_write_b16 v77, v67
	v_min_f32_e64 v67, -v38, s40
	v_mul_f32_e32 v67, 0x3fb8aa3b, v67
	v_exp_f32_e32 v67, v67
	v_sub_f32_e32 v62, 1.0, v62
	v_exp_f32_e32 v59, v59
	v_mul_f32_e32 v49, 0x3fb8aa3b, v49
	v_mul_f32_e32 v67, v76, v67
	v_cvt_pk_bf16_f32 v67, v67, s0
	ds_write_b16 v77, v67 offset:10240
	v_sub_f32_e32 v67, v38, v38
	v_mul_f32_e32 v67, 0x3fb8aa3b, v67
	v_exp_f32_e32 v67, v67
	v_sub_f32_e32 v59, 1.0, v59
	v_exp_f32_e32 v49, v49
	v_mul_f32_e32 v47, 0x3fb8aa3b, v47
	v_mul_f32_e32 v67, v76, v67
	v_cvt_pk_bf16_f32 v67, v67, s0
	ds_write_b16 v77, v67 offset:20480
	v_sub_f32_e32 v76, 1.0, v66
	v_mad_u64_u32 v[66:67], s[4:5], v64, s39, v[0:1]
	v_mul_f32_e32 v0, 0x3fb8aa3b, v75
	v_exp_f32_e32 v0, v0
	v_sub_f32_e32 v49, 1.0, v49
	v_exp_f32_e32 v47, v47
	v_mul_f32_e32 v42, 0x3fb8aa3b, v42
	v_mul_f32_e32 v0, v0, v63
	v_cvt_pk_bf16_f32 v63, v0, s0
	v_lshl_add_u32 v0, v66, 1, 32
	ds_write_b16 v0, v63
	v_min_f32_e64 v63, -v75, s40
	v_mul_f32_e32 v63, 0x3fb8aa3b, v63
	v_exp_f32_e32 v63, v63
	v_sub_f32_e32 v47, 1.0, v47
	v_exp_f32_e32 v42, v42
	v_mul_f32_e32 v35, 0x3fb8aa3b, v35
	v_mul_f32_e32 v63, v76, v63
	v_cvt_pk_bf16_f32 v63, v63, s0
	ds_write_b16 v0, v63 offset:10240
	v_sub_f32_e32 v63, v38, v75
	v_mul_f32_e32 v63, 0x3fb8aa3b, v63
	v_exp_f32_e32 v63, v63
	v_sub_f32_e32 v42, 1.0, v42
	v_exp_f32_e32 v35, v35
	v_mul_f32_e32 v33, 0x3fb8aa3b, v33
	v_mul_f32_e32 v63, v76, v63
	v_cvt_pk_bf16_f32 v63, v63, s0
	ds_write_b16 v0, v63 offset:20480
	v_mul_f32_e32 v63, 0x3fb8aa3b, v74
	v_exp_f32_e32 v63, v63
	v_sub_f32_e32 v35, 1.0, v35
	v_exp_f32_e32 v33, v33
	v_mul_f32_e32 v31, 0x3fb8aa3b, v31
	v_mul_f32_e32 v60, v63, v60
	v_cvt_pk_bf16_f32 v60, v60, s0
	ds_write_b16 v0, v60 offset:160
	v_min_f32_e64 v60, -v74, s40
	v_mul_f32_e32 v60, 0x3fb8aa3b, v60
	v_exp_f32_e32 v60, v60
	v_sub_f32_e32 v33, 1.0, v33
	v_exp_f32_e32 v31, v31
	v_mul_f32_e32 v29, 0x3fb8aa3b, v29
	v_mul_f32_e32 v60, v62, v60
	v_cvt_pk_bf16_f32 v60, v60, s0
	ds_write_b16 v0, v60 offset:10400
	v_sub_f32_e32 v60, v38, v74
	v_mul_f32_e32 v60, 0x3fb8aa3b, v60
	v_exp_f32_e32 v60, v60
	v_sub_f32_e32 v31, 1.0, v31
	v_exp_f32_e32 v29, v29
	v_mul_f32_e32 v27, 0x3fb8aa3b, v27
	v_mul_f32_e32 v60, v62, v60
	v_cvt_pk_bf16_f32 v60, v60, s0
	ds_write_b16 v0, v60 offset:20640
	v_mul_f32_e32 v60, 0x3fb8aa3b, v73
	v_exp_f32_e32 v60, v60
	v_sub_f32_e32 v29, 1.0, v29
	v_exp_f32_e32 v27, v27
	v_mul_f32_e32 v22, 0x3fb8aa3b, v22
	v_mul_f32_e32 v51, v60, v51
	v_cvt_pk_bf16_f32 v51, v51, s0
	ds_write_b16 v0, v51 offset:320
	v_min_f32_e64 v51, -v73, s40
	v_mul_f32_e32 v51, 0x3fb8aa3b, v51
	v_exp_f32_e32 v51, v51
	v_sub_f32_e32 v27, 1.0, v27
	v_exp_f32_e32 v22, v22
	v_mul_f32_e32 v51, v59, v51
	v_cvt_pk_bf16_f32 v51, v51, s0
	ds_write_b16 v0, v51 offset:10560
	v_sub_f32_e32 v51, v38, v73
	v_mul_f32_e32 v51, 0x3fb8aa3b, v51
	v_exp_f32_e32 v51, v51
	v_sub_f32_e32 v22, 1.0, v22
	v_mul_f32_e32 v51, v59, v51
	v_cvt_pk_bf16_f32 v51, v51, s0
	ds_write_b16 v0, v51 offset:20800
	v_mul_f32_e32 v51, 0x3fb8aa3b, v72
	v_exp_f32_e32 v51, v51
	s_nop 0
	v_mul_f32_e32 v48, v51, v48
	v_cvt_pk_bf16_f32 v48, v48, s0
	ds_write_b16 v0, v48 offset:480
	v_min_f32_e64 v48, -v72, s40
	v_mul_f32_e32 v48, 0x3fb8aa3b, v48
	v_exp_f32_e32 v48, v48
	v_lshl_add_u32 v51, v25, 5, 32
	v_mul_f32_e32 v48, v49, v48
	v_cvt_pk_bf16_f32 v48, v48, s0
	ds_write_b16 v0, v48 offset:10720
	v_sub_f32_e32 v48, v38, v72
	v_mul_f32_e32 v48, 0x3fb8aa3b, v48
	v_exp_f32_e32 v48, v48
	s_nop 0
	v_mul_f32_e32 v48, v49, v48
	v_cvt_pk_bf16_f32 v48, v48, s0
	ds_write_b16 v0, v48 offset:20960
	v_mul_f32_e32 v48, 0x3fb8aa3b, v71
	v_exp_f32_e32 v48, v48
	s_nop 0
	v_mul_f32_e32 v45, v48, v45
	v_cvt_pk_bf16_f32 v45, v45, s0
	ds_write_b16 v0, v45 offset:640
	v_min_f32_e64 v45, -v71, s40
	v_mul_f32_e32 v45, 0x3fb8aa3b, v45
	v_exp_f32_e32 v45, v45
	s_nop 0
	v_mul_f32_e32 v45, v47, v45
	v_cvt_pk_bf16_f32 v45, v45, s0
	ds_write_b16 v0, v45 offset:10880
	v_sub_f32_e32 v45, v38, v71
	v_mul_f32_e32 v45, 0x3fb8aa3b, v45
	v_exp_f32_e32 v45, v45
	s_nop 0
	v_mul_f32_e32 v45, v47, v45
	v_cvt_pk_bf16_f32 v45, v45, s0
	ds_write_b16 v0, v45 offset:21120
	v_mul_f32_e32 v45, 0x3fb8aa3b, v70
	v_exp_f32_e32 v45, v45
	s_nop 0
	v_mul_f32_e32 v36, v45, v36
	v_cvt_pk_bf16_f32 v36, v36, s0
	ds_write_b16 v0, v36 offset:800
	v_min_f32_e64 v36, -v70, s40
	v_mul_f32_e32 v36, 0x3fb8aa3b, v36
	v_exp_f32_e32 v36, v36
	v_lshlrev_b32_e32 v45, 3, v26
	v_mul_f32_e32 v36, v42, v36
	v_cvt_pk_bf16_f32 v36, v36, s0
	ds_write_b16 v0, v36 offset:11040
	v_sub_f32_e32 v36, v38, v70
	v_mul_f32_e32 v36, 0x3fb8aa3b, v36
	v_exp_f32_e32 v36, v36
	s_nop 0
	v_mul_f32_e32 v36, v42, v36
	v_cvt_pk_bf16_f32 v36, v36, s0
	ds_write_b16 v0, v36 offset:21280
	v_mul_f32_e32 v36, 0x3fb8aa3b, v69
	v_exp_f32_e32 v36, v36
	s_nop 0
	v_mul_f32_e32 v34, v36, v34
	v_cvt_pk_bf16_f32 v34, v34, s0
	ds_write_b16 v0, v34 offset:960
	v_min_f32_e64 v34, -v69, s40
	v_mul_f32_e32 v34, 0x3fb8aa3b, v34
	v_exp_f32_e32 v34, v34
	s_nop 0
	v_mul_f32_e32 v34, v35, v34
	v_cvt_pk_bf16_f32 v34, v34, s0
	ds_write_b16 v0, v34 offset:11200
	v_sub_f32_e32 v34, v38, v69
	v_mul_f32_e32 v34, 0x3fb8aa3b, v34
	v_exp_f32_e32 v34, v34
	s_nop 0
	v_mul_f32_e32 v34, v35, v34
	v_cvt_pk_bf16_f32 v34, v34, s0
	ds_write_b16 v0, v34 offset:21440
	v_mul_f32_e32 v34, 0x3fb8aa3b, v68
	v_exp_f32_e32 v34, v34
	s_nop 0
	v_mul_f32_e32 v32, v34, v32
	v_cvt_pk_bf16_f32 v32, v32, s0
	ds_write_b16 v0, v32 offset:1120
	v_min_f32_e64 v32, -v68, s40
	v_mul_f32_e32 v32, 0x3fb8aa3b, v32
	v_exp_f32_e32 v32, v32
	s_nop 0
	v_mul_f32_e32 v32, v33, v32
	v_cvt_pk_bf16_f32 v32, v32, s0
	ds_write_b16 v0, v32 offset:11360
	v_sub_f32_e32 v32, v38, v68
	v_mul_f32_e32 v32, 0x3fb8aa3b, v32
	v_exp_f32_e32 v32, v32
	s_nop 0
	v_mul_f32_e32 v32, v33, v32
	v_cvt_pk_bf16_f32 v32, v32, s0
	ds_write_b16 v0, v32 offset:21600
	v_mul_f32_e32 v32, 0x3fb8aa3b, v65
	v_exp_f32_e32 v32, v32
	s_nop 0
	v_mul_f32_e32 v30, v32, v30
	v_cvt_pk_bf16_f32 v30, v30, s0
	ds_write_b16 v0, v30 offset:1280
	v_min_f32_e64 v30, -v65, s40
	v_mul_f32_e32 v30, 0x3fb8aa3b, v30
	v_exp_f32_e32 v30, v30
	s_nop 0
	v_mul_f32_e32 v30, v31, v30
	v_cvt_pk_bf16_f32 v30, v30, s0
	ds_write_b16 v0, v30 offset:11520
	v_sub_f32_e32 v30, v38, v65
	v_mul_f32_e32 v30, 0x3fb8aa3b, v30
	v_exp_f32_e32 v30, v30
	s_nop 0
	v_mul_f32_e32 v30, v31, v30
	v_cvt_pk_bf16_f32 v30, v30, s0
	ds_write_b16 v0, v30 offset:21760
	v_mul_f32_e32 v30, 0x3fb8aa3b, v61
	v_exp_f32_e32 v30, v30
	s_nop 0
	v_mul_f32_e32 v28, v30, v28
	v_cvt_pk_bf16_f32 v28, v28, s0
	ds_write_b16 v0, v28 offset:1440
	v_min_f32_e64 v28, -v61, s40
	v_mul_f32_e32 v28, 0x3fb8aa3b, v28
	v_exp_f32_e32 v28, v28
	s_nop 0
	v_mul_f32_e32 v28, v29, v28
	v_cvt_pk_bf16_f32 v28, v28, s0
	ds_write_b16 v0, v28 offset:11680
	v_sub_f32_e32 v28, v38, v61
	v_mul_f32_e32 v28, 0x3fb8aa3b, v28
	v_exp_f32_e32 v28, v28
	s_nop 0
	v_mul_f32_e32 v28, v29, v28
	v_cvt_pk_bf16_f32 v28, v28, s0
	ds_write_b16 v0, v28 offset:21920
	v_mul_f32_e32 v28, 0x3fb8aa3b, v50
	v_exp_f32_e32 v28, v28
	s_nop 0
	v_mul_f32_e32 v23, v28, v23
	v_cvt_pk_bf16_f32 v23, v23, s0
	ds_write_b16 v0, v23 offset:1600
	v_min_f32_e64 v23, -v50, s40
	v_mul_f32_e32 v23, 0x3fb8aa3b, v23
	v_exp_f32_e32 v23, v23
	s_nop 0
	v_mul_f32_e32 v23, v27, v23
	v_cvt_pk_bf16_f32 v23, v23, s0
	ds_write_b16 v0, v23 offset:11840
	v_sub_f32_e32 v23, v38, v50
	v_mul_f32_e32 v23, 0x3fb8aa3b, v23
	v_exp_f32_e32 v23, v23
	s_nop 0
	v_mul_f32_e32 v23, v27, v23
	v_cvt_pk_bf16_f32 v23, v23, s0
	ds_write_b16 v0, v23 offset:22080
	v_mul_f32_e32 v23, 0x3fb8aa3b, v46
	v_exp_f32_e32 v23, v23
	v_lshlrev_b32_e32 v27, 2, v24
	v_and_b32_e32 v50, 12, v27
	v_mul_f32_e32 v1, v23, v1
	v_cvt_pk_bf16_f32 v1, v1, s0
	ds_write_b16 v0, v1 offset:1760
	v_min_f32_e64 v1, -v46, s40
	v_mul_f32_e32 v1, 0x3fb8aa3b, v1
	v_exp_f32_e32 v1, v1
	s_nop 0
	v_mul_f32_e32 v1, v22, v1
	v_cvt_pk_bf16_f32 v1, v1, s0
	ds_write_b16 v0, v1 offset:12000
	v_sub_f32_e32 v1, v38, v46
	v_mul_f32_e32 v1, 0x3fb8aa3b, v1
	v_exp_f32_e32 v1, v1
	s_nop 0
	v_mul_f32_e32 v1, v22, v1
	v_cvt_pk_bf16_f32 v1, v1, s0
	ds_write_b16 v0, v1 offset:22240
	v_mul_f32_e32 v1, 0x3fb8aa3b, v19
	v_mul_f32_e32 v19, 0x3fb8aa3b, v44
	v_exp_f32_e32 v19, v19
	v_exp_f32_e32 v1, v1
	v_mul_f32_e32 v2, v19, v2
	v_cvt_pk_bf16_f32 v2, v2, s0
	ds_write_b16 v0, v2 offset:1920
	v_min_f32_e64 v2, -v44, s40
	v_mul_f32_e32 v2, 0x3fb8aa3b, v2
	v_exp_f32_e32 v2, v2
	v_sub_f32_e32 v1, 1.0, v1
	v_mul_f32_e32 v2, v1, v2
	v_cvt_pk_bf16_f32 v2, v2, s0
	ds_write_b16 v0, v2 offset:12160
	v_sub_f32_e32 v2, v38, v44
	v_mul_f32_e32 v2, 0x3fb8aa3b, v2
	v_exp_f32_e32 v2, v2
	v_lshlrev_b32_e32 v44, 2, v26
	v_mul_f32_e32 v1, v1, v2
	v_mul_f32_e32 v2, 0x3fb8aa3b, v39
	v_exp_f32_e32 v2, v2
	v_cvt_pk_bf16_f32 v1, v1, s0
	ds_write_b16 v0, v1 offset:22400
	v_mul_f32_e32 v1, 0x3fb8aa3b, v21
	v_mul_f32_e32 v2, v2, v18
	v_cvt_pk_bf16_f32 v2, v2, s0
	ds_write_b16 v0, v2 offset:2080
	v_min_f32_e64 v2, -v39, s40
	v_exp_f32_e32 v1, v1
	v_mul_f32_e32 v2, 0x3fb8aa3b, v2
	v_exp_f32_e32 v2, v2
	v_sub_f32_e32 v1, 1.0, v1
	v_mul_f32_e32 v2, v1, v2
	v_cvt_pk_bf16_f32 v2, v2, s0
	ds_write_b16 v0, v2 offset:12320
	v_sub_f32_e32 v2, v38, v39
	v_mul_f32_e32 v2, 0x3fb8aa3b, v2
	v_exp_f32_e32 v2, v2
	s_nop 0
	v_mul_f32_e32 v1, v1, v2
	v_mul_f32_e32 v2, 0x3fb8aa3b, v17
	v_exp_f32_e32 v2, v2
	v_cvt_pk_bf16_f32 v1, v1, s0
	ds_write_b16 v0, v1 offset:22560
	v_mul_f32_e32 v1, 0x3fb8aa3b, v16
	v_mul_f32_e32 v2, v2, v37
	v_cvt_pk_bf16_f32 v2, v2, s0
	ds_write_b16 v0, v2 offset:2240
	v_min_f32_e64 v2, -v17, s40
	v_exp_f32_e32 v1, v1
	v_mul_f32_e32 v2, 0x3fb8aa3b, v2
	v_exp_f32_e32 v2, v2
	v_sub_f32_e32 v1, 1.0, v1
	v_mul_f32_e32 v2, v1, v2
	v_cvt_pk_bf16_f32 v2, v2, s0
	ds_write_b16 v0, v2 offset:12480
	v_sub_f32_e32 v2, v38, v17
	v_mul_f32_e32 v2, 0x3fb8aa3b, v2
	v_exp_f32_e32 v2, v2
	s_nop 0
	v_mul_f32_e32 v1, v1, v2
	v_cvt_pk_bf16_f32 v1, v1, s0
	ds_write_b16 v0, v1 offset:22720
	v_add_u32_e32 v0, 32, v27
	v_ashrrev_i32_e32 v1, 3, v24
	ds_write_b32 v0, v43 offset:40960
	v_lshlrev_b32_e32 v0, 4, v24
	v_mad_i64_i32 v[16:17], s[4:5], v1, s48, v[40:41]
	v_and_b32_e32 v2, 0x70, v0
	v_lshl_add_u64 v[16:17], v[16:17], 0, s[22:23]
	v_lshl_add_u64 v[16:17], v[16:17], 0, v[2:3]
	s_waitcnt vmcnt(5)
	v_mov_b32_e32 v16, v140
	v_mov_b32_e32 v17, v141
	v_mov_b32_e32 v18, v142
	v_mov_b32_e32 v19, v143
	v_add_u32_e32 v0, 32, v2
	v_mad_u64_u32 v[22:23], s[4:5], v1, s42, v[0:1]
	v_add_u32_e32 v1, 0x100, v24
	v_ashrrev_i32_e32 v1, 3, v1
	s_waitcnt vmcnt(0)
	ds_write_b128 v22, v[16:19] offset:30720
	v_mad_i64_i32 v[16:17], s[4:5], v1, s48, v[40:41]
	v_lshl_add_u64 v[16:17], v[16:17], 0, s[22:23]
	v_lshl_add_u64 v[16:17], v[16:17], 0, v[2:3]
	v_mov_b32_e32 v16, v144
	v_mov_b32_e32 v17, v145
	v_mov_b32_e32 v18, v146
	v_mov_b32_e32 v19, v147
	v_mad_u64_u32 v[0:1], s[4:5], v1, s42, v[0:1]
	v_and_b32_e32 v2, 15, v24
	s_add_u32 s4, s12, 0x110000
	s_addc_u32 s5, s13, 0
	v_cmp_lt_u32_e32 vcc, v44, v2
	s_waitcnt vmcnt(0)
	ds_write_b128 v0, v[16:19] offset:30720
	v_or_b32_e32 v0, v20, v2
	v_lshl_add_u32 v0, v26, 8, v0
	v_ashrrev_i32_e32 v1, 31, v0
	v_lshl_add_u64 v[16:17], v[0:1], 2, s[4:5]
	s_waitcnt lgkmcnt(0)
	s_barrier
	s_waitcnt vmcnt(5)
	v_mov_b32_e32 v20, v164
	v_add_u32_e32 v16, 64, v0
	v_ashrrev_i32_e32 v17, 31, v16
	v_lshl_add_u64 v[16:17], v[16:17], 2, s[4:5]
	v_mov_b32_e32 v21, v165
	v_add_u32_e32 v16, 0x80, v0
	v_ashrrev_i32_e32 v17, 31, v16
	v_lshl_add_u64 v[16:17], v[16:17], 2, s[4:5]
	v_mov_b32_e32 v22, v166
	v_add_u32_e32 v16, 0xc0, v0
	v_ashrrev_i32_e32 v17, 31, v16
	v_lshl_add_u64 v[16:17], v[16:17], 2, s[4:5]
	v_mov_b32_e32 v23, v167
	v_add_u32_e32 v16, 0x400, v0
	v_ashrrev_i32_e32 v17, 31, v16
	v_lshl_add_u64 v[16:17], v[16:17], 2, s[4:5]
	v_mov_b32_e32 v28, v168
	v_add_u32_e32 v16, 0x440, v0
	v_ashrrev_i32_e32 v17, 31, v16
	v_lshl_add_u64 v[16:17], v[16:17], 2, s[4:5]
	v_mov_b32_e32 v29, v169
	v_add_u32_e32 v16, 0x480, v0
	v_ashrrev_i32_e32 v17, 31, v16
	v_lshl_add_u64 v[16:17], v[16:17], 2, s[4:5]
	v_mov_b32_e32 v34, v170
	v_add_u32_e32 v16, 0x4c0, v0
	v_ashrrev_i32_e32 v17, 31, v16
	v_lshl_add_u64 v[16:17], v[16:17], 2, s[4:5]
	v_mov_b32_e32 v35, v171
	v_add_u32_e32 v16, 0x800, v0
	v_ashrrev_i32_e32 v17, 31, v16
	v_lshl_add_u64 v[16:17], v[16:17], 2, s[4:5]
	v_mov_b32_e32 v36, v172
	v_add_u32_e32 v16, 0x840, v0
	v_ashrrev_i32_e32 v17, 31, v16
	v_lshl_add_u64 v[16:17], v[16:17], 2, s[4:5]
	v_mov_b32_e32 v37, v173
	v_add_u32_e32 v16, 0x880, v0
	v_ashrrev_i32_e32 v17, 31, v16
	v_lshl_add_u64 v[16:17], v[16:17], 2, s[4:5]
	v_mov_b32_e32 v38, v174
	v_add_u32_e32 v16, 0x8c0, v0
	v_ashrrev_i32_e32 v17, 31, v16
	v_lshl_add_u64 v[16:17], v[16:17], 2, s[4:5]
	v_mov_b32_e32 v39, v175
	v_add_u32_e32 v16, 0xc00, v0
	v_ashrrev_i32_e32 v17, 31, v16
	v_lshl_add_u64 v[16:17], v[16:17], 2, s[4:5]
	v_mov_b32_e32 v40, v176
	v_add_u32_e32 v16, 0xc40, v0
	v_ashrrev_i32_e32 v17, 31, v16
	v_lshl_add_u64 v[16:17], v[16:17], 2, s[4:5]
	v_mov_b32_e32 v41, v177
	v_add_u32_e32 v16, 0xc80, v0
	v_add_u32_e32 v0, 0xcc0, v0
	v_ashrrev_i32_e32 v17, 31, v16
	v_ashrrev_i32_e32 v1, 31, v0
	v_lshl_add_u64 v[16:17], v[16:17], 2, s[4:5]
	v_lshl_add_u64 v[0:1], v[0:1], 2, s[4:5]
	v_mov_b32_e32 v42, v178
	v_mov_b32_e32 v43, v179
	v_bfe_u32 v0, v24, 2, 2
	v_and_b32_e32 v24, 48, v24
	v_mul_u32_u24_e32 v16, 0x50, v2
	v_add_u32_e32 v61, 32, v24
	v_lshlrev_b32_e32 v25, 1, v16
	v_add_u32_e32 v48, v61, v25
	ds_read_b128 v[16:19], v48 offset:17920
	v_add3_u32 v60, 32, v25, v24
	v_or_b32_e32 v49, v44, v0
	ds_read_b128 v[24:27], v60 offset:7680
	v_mul_u32_u24_e32 v0, 0x50, v49
	v_or_b32_e32 v0, v0, v50
	v_lshlrev_b32_e32 v46, 1, v0
	v_add_u32_e32 v63, v51, v46
	ds_read_b64_tr_b16 v[0:1], v63 offset:38400
	s_waitcnt lgkmcnt(1)
	v_mfma_f32_16x16x32_bf16 v[16:19], v[16:19], v[24:27], 0
	ds_read_b128 v[24:27], v48 offset:17984
	ds_read_b128 v[30:33], v60 offset:7744
	v_sub_u32_e32 v59, v60, v45
	v_add_u32_e32 v62, 32, v46
	s_waitcnt lgkmcnt(0)
	v_mfma_f32_16x16x32_bf16 v[16:19], v[24:27], v[30:33], v[16:19]
	v_or_b32_e32 v24, 1, v44
	v_cmp_lt_u32_e64 s[4:5], v24, v2
	v_or_b32_e32 v24, 2, v44
	v_cmp_lt_u32_e64 s[6:7], v24, v2
	v_or_b32_e32 v24, 3, v44
	v_cmp_lt_u32_e64 s[8:9], v24, v2
	s_nop 1
	v_cndmask_b32_e64 v16, v16, 0, vcc
	v_cndmask_b32_e64 v17, v17, 0, s[4:5]
	v_cndmask_b32_e64 v18, v18, 0, s[6:7]
	v_cndmask_b32_e64 v2, v19, 0, s[8:9]
	v_cvt_pk_bf16_f32 v16, v16, v17
	v_cvt_pk_bf16_f32 v17, v18, v2
	v_mov_b32_e32 v2, v3
	v_add_u32_e32 v44, 0x1800, v59
	v_mov_b32_e32 v18, v3
	v_mov_b32_e32 v19, v3
	s_waitcnt vmcnt(14)
	v_cvt_pk_bf16_f32 v24, v20, v21
	s_waitcnt vmcnt(12)
	v_cvt_pk_bf16_f32 v25, v22, v23
	s_waitcnt vmcnt(10)
	v_cvt_pk_bf16_f32 v26, v28, v29
	ds_read2_b64 v[30:33], v44 offset0:192 offset1:196
	v_mfma_f32_16x16x32_bf16 v[16:19], v[0:3], v[16:19], 0
	v_add_u32_e32 v64, 0x1000, v59
	s_waitcnt vmcnt(8)
	v_cvt_pk_bf16_f32 v27, v34, v35
	s_waitcnt lgkmcnt(0)
	s_nop 0
	v_mfma_f32_16x16x32_bf16 v[16:19], v[24:27], v[30:33], v[16:19]
	ds_read2_b64 v[30:33], v44 offset0:200 offset1:204
	s_waitcnt vmcnt(6)
	v_cvt_pk_bf16_f32 v24, v36, v37
	s_waitcnt vmcnt(4)
	v_cvt_pk_bf16_f32 v25, v38, v39
	s_waitcnt vmcnt(2)
	v_cvt_pk_bf16_f32 v26, v40, v41
	s_waitcnt vmcnt(0)
	v_cvt_pk_bf16_f32 v27, v42, v43
	s_waitcnt lgkmcnt(0)
	s_nop 0
	v_mfma_f32_16x16x32_bf16 v[16:19], v[24:27], v[30:33], v[16:19]
	ds_read_b128 v[24:27], v61 offset:41728
	ds_read_b64_tr_b16 v[32:33], v62 offset:28224
	v_mov_b32_e32 v30, v3
	v_mov_b32_e32 v31, v3
	s_waitcnt lgkmcnt(1)
	v_pk_mul_f32 v[20:21], v[20:21], v[24:25]
	ds_read_b64_tr_b16 v[24:25], v62 offset:28160
	v_pk_mul_f32 v[22:23], v[22:23], v[26:27]
	v_mov_b32_e32 v26, v3
	v_mov_b32_e32 v27, v3
	s_waitcnt lgkmcnt(0)
	s_nop 0
	v_mfma_f32_16x16x32_bf16 v[24:27], v[24:27], v[0:3], v[20:23]
	s_nop 2
	ds_read_b128 v[20:23], v61 offset:41792
	s_waitcnt lgkmcnt(0)
	v_pk_mul_f32 v[20:21], v[28:29], v[20:21]
	ds_read_b64_tr_b16 v[28:29], v62 offset:28192
	v_pk_mul_f32 v[22:23], v[34:35], v[22:23]
	v_mov_b32_e32 v34, v3
	v_mov_b32_e32 v35, v3
	s_waitcnt lgkmcnt(0)
	v_mfma_f32_16x16x32_bf16 v[28:31], v[28:31], v[0:3], v[20:23]
	s_nop 2
	ds_read_b128 v[20:23], v61 offset:41856
	s_waitcnt lgkmcnt(0)
	v_pk_mul_f32 v[20:21], v[36:37], v[20:21]
	v_pk_mul_f32 v[22:23], v[38:39], v[22:23]
	ds_read_b64_tr_b16 v[36:37], v62 offset:28256
	v_mov_b32_e32 v38, v3
	v_mfma_f32_16x16x32_bf16 v[32:35], v[32:35], v[0:3], v[20:23]
	v_mov_b32_e32 v39, v3
	s_nop 1
	ds_read_b128 v[20:23], v61 offset:41920
	s_waitcnt lgkmcnt(0)
	v_pk_mul_f32 v[20:21], v[40:41], v[20:21]
	v_pk_mul_f32 v[22:23], v[42:43], v[22:23]
	s_nop 1
	v_mfma_f32_16x16x32_bf16 v[36:39], v[36:39], v[0:3], v[20:23]
	ds_read_b64_tr_b16 v[0:1], v63 offset:35840
	s_nop 1
	ds_read_b128 v[20:23], v48 offset:15360
	ds_read_b128 v[40:43], v60 offset:5120
	s_waitcnt lgkmcnt(0)
	v_mfma_f32_16x16x32_bf16 v[20:23], v[20:23], v[40:43], 0
	ds_read_b128 v[40:43], v48 offset:15424
	ds_read_b128 v[44:47], v60 offset:5184
	s_waitcnt lgkmcnt(0)
	v_mfma_f32_16x16x32_bf16 v[20:23], v[40:43], v[44:47], v[20:23]
	v_cvt_pk_bf16_f32 v40, v24, v25
	v_cvt_pk_bf16_f32 v41, v26, v27
	v_cvt_pk_bf16_f32 v42, v28, v29
	s_nop 4
	v_cndmask_b32_e64 v2, v20, 0, vcc
	v_cndmask_b32_e64 v20, v21, 0, s[4:5]
	v_cvt_pk_bf16_f32 v20, v2, v20
	v_mov_b32_e32 v2, v3
	v_cndmask_b32_e64 v21, v22, 0, s[6:7]
	v_cndmask_b32_e64 v22, v23, 0, s[8:9]
	v_cvt_pk_bf16_f32 v21, v21, v22
	v_mov_b32_e32 v22, v3
	v_mov_b32_e32 v23, v3
	v_cvt_pk_bf16_f32 v43, v30, v31
	ds_read2_b64 v[44:47], v64 offset0:128 offset1:132
	v_mfma_f32_16x16x32_bf16 v[20:23], v[0:3], v[20:23], 0
	s_waitcnt lgkmcnt(0)
	v_mfma_f32_16x16x32_bf16 v[20:23], v[40:43], v[44:47], v[20:23]
	v_cvt_pk_bf16_f32 v40, v32, v33
	v_cvt_pk_bf16_f32 v41, v34, v35
	v_cvt_pk_bf16_f32 v42, v36, v37
	v_cvt_pk_bf16_f32 v43, v38, v39
	ds_read2_b64 v[44:47], v64 offset0:136 offset1:140
	s_waitcnt lgkmcnt(0)
	v_mfma_f32_16x16x32_bf16 v[20:23], v[40:43], v[44:47], v[20:23]
	ds_read_b128 v[40:43], v61 offset:41472
	s_waitcnt lgkmcnt(0)
	v_pk_mul_f32 v[24:25], v[24:25], v[40:41]
	ds_read_b64_tr_b16 v[40:41], v62 offset:25600
	v_pk_mul_f32 v[26:27], v[26:27], v[42:43]
	v_mov_b32_e32 v42, v3
	v_mov_b32_e32 v43, v3
	s_waitcnt lgkmcnt(0)
	s_nop 0
	v_mfma_f32_16x16x32_bf16 v[40:43], v[40:43], v[0:3], v[24:27]
	s_nop 2
	ds_read_b128 v[24:27], v61 offset:41536
	s_waitcnt lgkmcnt(0)
	v_pk_mul_f32 v[24:25], v[28:29], v[24:25]
	ds_read_b64_tr_b16 v[28:29], v62 offset:25632
	v_pk_mul_f32 v[26:27], v[30:31], v[26:27]
	v_mov_b32_e32 v30, v3
	v_mov_b32_e32 v31, v3
	s_waitcnt lgkmcnt(0)
	s_nop 0
	v_mfma_f32_16x16x32_bf16 v[28:31], v[28:31], v[0:3], v[24:27]
	s_nop 2
	ds_read_b128 v[24:27], v61 offset:41600
	s_waitcnt lgkmcnt(0)
	v_pk_mul_f32 v[24:25], v[32:33], v[24:25]
	ds_read_b64_tr_b16 v[32:33], v62 offset:25664
	v_pk_mul_f32 v[26:27], v[34:35], v[26:27]
	v_mov_b32_e32 v34, v3
	v_mov_b32_e32 v35, v3
	s_waitcnt lgkmcnt(0)
	s_nop 0
	v_mfma_f32_16x16x32_bf16 v[32:35], v[32:35], v[0:3], v[24:27]
	s_nop 2
	ds_read_b128 v[24:27], v61 offset:41664
	s_waitcnt lgkmcnt(0)
	v_pk_mul_f32 v[24:25], v[36:37], v[24:25]
	ds_read_b64_tr_b16 v[36:37], v62 offset:25696
	v_pk_mul_f32 v[26:27], v[38:39], v[26:27]
	v_mov_b32_e32 v38, v3
	v_mov_b32_e32 v39, v3
	s_waitcnt lgkmcnt(0)
	s_nop 0
	v_mfma_f32_16x16x32_bf16 v[44:47], v[36:39], v[0:3], v[24:27]
	ds_read_b64_tr_b16 v[0:1], v63 offset:33280
	s_nop 1
	ds_read_b128 v[24:27], v48 offset:12800
	ds_read_b128 v[36:39], v60 offset:2560
	v_add_u32_e32 v63, 0x800, v59
	s_waitcnt lgkmcnt(0)
	v_mfma_f32_16x16x32_bf16 v[24:27], v[24:27], v[36:39], 0
	ds_read_b128 v[36:39], v48 offset:12864
	ds_read_b128 v[64:67], v60 offset:2624
	s_waitcnt lgkmcnt(0)
	v_mfma_f32_16x16x32_bf16 v[24:27], v[36:39], v[64:67], v[24:27]
	v_cvt_pk_bf16_f32 v36, v40, v41
	v_cvt_pk_bf16_f32 v37, v42, v43
	v_cvt_pk_bf16_f32 v38, v28, v29
	s_nop 4
	v_cndmask_b32_e64 v2, v24, 0, vcc
	v_cndmask_b32_e64 v24, v25, 0, s[4:5]
	v_cvt_pk_bf16_f32 v24, v2, v24
	v_mov_b32_e32 v2, v3
	v_cndmask_b32_e64 v25, v26, 0, s[6:7]
	v_cndmask_b32_e64 v26, v27, 0, s[8:9]
	v_cvt_pk_bf16_f32 v25, v25, v26
	v_mov_b32_e32 v26, v3
	v_mov_b32_e32 v27, v3
	v_cvt_pk_bf16_f32 v39, v30, v31
	ds_read2_b64 v[64:67], v63 offset0:64 offset1:68
	v_mfma_f32_16x16x32_bf16 v[24:27], v[0:3], v[24:27], 0
	s_waitcnt lgkmcnt(0)
	v_mfma_f32_16x16x32_bf16 v[24:27], v[36:39], v[64:67], v[24:27]
	v_cvt_pk_bf16_f32 v36, v32, v33
	v_cvt_pk_bf16_f32 v37, v34, v35
	v_cvt_pk_bf16_f32 v38, v44, v45
	v_cvt_pk_bf16_f32 v39, v46, v47
	ds_read2_b64 v[64:67], v63 offset0:72 offset1:76
	s_waitcnt lgkmcnt(0)
	v_mfma_f32_16x16x32_bf16 v[24:27], v[36:39], v[64:67], v[24:27]
	ds_read_b128 v[36:39], v61 offset:41216
	v_mov_b32_e32 v66, v3
	v_mov_b32_e32 v67, v3
	s_waitcnt lgkmcnt(0)
	v_pk_mul_f32 v[38:39], v[42:43], v[38:39]
	v_mov_b32_e32 v42, v3
	v_mov_b32_e32 v43, v3
	v_pk_mul_f32 v[36:37], v[40:41], v[36:37]
	ds_read_b64_tr_b16 v[40:41], v62 offset:23040
	ds_read_b64_tr_b16 v[64:65], v62 offset:23072
	s_waitcnt lgkmcnt(1)
	v_mfma_f32_16x16x32_bf16 v[36:39], v[40:43], v[0:3], v[36:39]
	ds_read_b128 v[40:43], v61 offset:41280
	s_waitcnt lgkmcnt(0)
	v_pk_mul_f32 v[30:31], v[30:31], v[42:43]
	v_pk_mul_f32 v[28:29], v[28:29], v[40:41]
	s_nop 3
	v_cvt_pk_bf16_f32 v36, v36, v37
	v_cvt_pk_bf16_f32 v37, v38, v39
	v_mfma_f32_16x16x32_bf16 v[40:43], v[64:67], v[0:3], v[28:31]
	s_nop 2
	ds_read_b128 v[28:31], v61 offset:41344
	s_waitcnt lgkmcnt(0)
	v_pk_mul_f32 v[28:29], v[32:33], v[28:29]
	ds_read_b64_tr_b16 v[32:33], v62 offset:23104
	v_pk_mul_f32 v[30:31], v[34:35], v[30:31]
	v_mov_b32_e32 v34, v3
	v_mov_b32_e32 v35, v3
	v_cvt_pk_bf16_f32 v38, v40, v41
	v_cvt_pk_bf16_f32 v39, v42, v43
	s_waitcnt lgkmcnt(0)
	v_mfma_f32_16x16x32_bf16 v[28:31], v[32:35], v[0:3], v[28:31]
	ds_read_b128 v[32:35], v61 offset:41408
	s_waitcnt lgkmcnt(0)
	v_pk_mul_f32 v[32:33], v[44:45], v[32:33]
	ds_read_b64_tr_b16 v[44:45], v62 offset:23136
	v_pk_mul_f32 v[34:35], v[46:47], v[34:35]
	v_mov_b32_e32 v46, v3
	v_mov_b32_e32 v47, v3
	s_nop 0
	v_cvt_pk_bf16_f32 v28, v28, v29
	v_cvt_pk_bf16_f32 v29, v30, v31
	s_waitcnt lgkmcnt(0)
	v_mfma_f32_16x16x32_bf16 v[32:35], v[44:47], v[0:3], v[32:35]
	v_mul_u32_u24_e32 v0, 0xa0, v49
	v_lshlrev_b32_e32 v1, 1, v50
	v_add3_u32 v0, v51, v0, v1
	ds_read_b64_tr_b16 v[0:1], v0 offset:30720
	ds_read_b128 v[44:47], v48 offset:10240
	ds_read_b128 v[62:65], v60
	s_waitcnt lgkmcnt(0)
	v_mfma_f32_16x16x32_bf16 v[44:47], v[44:47], v[62:65], 0
	ds_read_b128 v[48:51], v48 offset:10304
	ds_read_b128 v[60:63], v60 offset:64
	ds_read2_b64 v[40:43], v59 offset1:4
	v_cvt_pk_bf16_f32 v30, v32, v33
	s_waitcnt lgkmcnt(1)
	v_mfma_f32_16x16x32_bf16 v[44:47], v[48:51], v[60:63], v[44:47]
	v_cvt_pk_bf16_f32 v31, v34, v35
	ds_read2_b64 v[32:35], v59 offset0:8 offset1:12
	s_nop 5
	v_cndmask_b32_e64 v2, v44, 0, vcc
	v_cndmask_b32_e64 v44, v45, 0, s[4:5]
	v_cvt_pk_bf16_f32 v44, v2, v44
	v_mov_b32_e32 v2, v3
	v_cndmask_b32_e64 v45, v46, 0, s[6:7]
	v_cndmask_b32_e64 v46, v47, 0, s[8:9]
	v_cvt_pk_bf16_f32 v45, v45, v46
	v_mov_b32_e32 v46, v3
	v_mov_b32_e32 v47, v3
	v_cmp_eq_u32_e32 vcc, 0, v57
	s_nop 0
	v_mfma_f32_16x16x32_bf16 v[44:47], v[0:3], v[44:47], 0
	v_and_b32_e32 v0, 0x3fffffc0, v58
	v_lshlrev_b32_e32 v0, 2, v0
	v_lshlrev_b32_e32 v1, 2, v56
	s_waitcnt lgkmcnt(1)
	v_mfma_f32_16x16x32_bf16 v[36:39], v[36:39], v[40:43], v[44:47]
	v_add3_u32 v2, 32, v0, v1
	v_mov_b32_e32 v1, v222
	s_waitcnt lgkmcnt(0)
	v_mfma_f32_16x16x32_bf16 v[30:33], v[28:31], v[32:35], v[36:39]
	v_lshlrev_b32_e32 v1, 2, v1
	v_bitop3_b32 v1, v1, 64, v229 bitop3:0x6c
	s_nop 5
	v_pk_add_f32 v[30:31], v[54:55], v[30:31]
	v_pk_add_f32 v[28:29], v[52:53], v[32:33]
	v_mul_f32_e32 v0, v31, v31
	v_fmac_f32_e32 v0, v30, v30
	v_fmac_f32_e32 v0, v28, v28
	v_fmac_f32_e32 v0, v29, v29
	ds_bpermute_b32 v1, v1, v0
	s_waitcnt lgkmcnt(0)
	v_add_f32_e32 v0, v0, v1
	v_mov_b32_e32 v1, v222
	s_nop 0
	v_lshlrev_b32_e32 v1, 2, v1
	v_bitop3_b32 v1, v1, s18, v229 bitop3:0x6c
	ds_bpermute_b32 v1, v1, v0
	s_and_saveexec_b64 s[4:5], vcc
	s_cbranch_execz .LBB0_906
	s_waitcnt lgkmcnt(0)
	v_add_f32_e32 v0, v0, v1
	ds_write_b32 v2, v0 offset:41984

.LBB0_913:
	s_and_b64 vcc, exec, s[0:1]
	s_cbranch_vccz .LBB0_896
	v_mov_b32_e32 v0, v222
	s_nop 0
	v_lshlrev_b32_e32 v1, 2, v0
	s_waitcnt vmcnt(8)
	v_and_b32_e32 v65, 0xfc, v1
	v_lshlrev_b32_e32 v1, 2, v65
	global_load_dwordx4 v[20:23], v1, s[52:53]
	global_load_dwordx4 v[16:19], v1, s[52:53] offset:1024
	global_load_dwordx4 v[12:15], v1, s[52:53] offset:2048
	global_load_dwordx4 v[8:11], v1, s[52:53] offset:3072
	global_load_dwordx4 v[4:7], v1, s[62:63]
	s_mul_hi_i32 s0, s10, 0x78787879
	s_lshr_b32 s1, s0, 31
	s_ashr_i32 s11, s0, 5
	s_add_i32 s11, s11, s1
	s_mul_i32 s0, s11, 0x44
	s_sub_i32 s9, s10, s0
	s_cmp_gt_i32 s9, 3
	s_cselect_b64 s[6:7], -1, 0
	s_cmp_lt_i32 s9, 4
	s_movk_i32 s0, 0x1100
	v_ashrrev_i32_e32 v1, 2, v0
	s_cselect_b32 s10, 0x100, s0
	s_cselect_b32 s12, 0, 0x100
	s_lshl_b32 s8, s9, 6
	v_and_b32_e32 v64, -16, v1
	v_add_u32_e32 v30, s8, v64
	v_lshlrev_b32_e32 v2, 1, v65
	v_cmp_lt_i32_e32 vcc, s12, v30
	v_cmp_ge_i32_e64 s[0:1], s10, v30
	s_mul_hi_i32 s5, s11, 0x1100
	s_mul_i32 s4, s11, 0x1100
	v_add_u32_e32 v32, -2, v30
	v_lshl_add_u64 v[28:29], s[24:25], 0, v[2:3]
	s_and_b64 s[38:39], vcc, s[0:1]
	v_mov_b64_e32 v[24:25], 0
	v_mov_b64_e32 v[26:27], 0
	s_and_saveexec_b64 s[0:1], s[38:39]
	s_cbranch_execz .LBB0_916
	v_mov_b32_e32 v33, v3
	v_lshl_add_u64 v[26:27], s[4:5], 0, v[32:33]
	v_mad_u64_u32 v[34:35], s[38:39], v26, s48, v[28:29]
	v_mov_b32_e32 v2, v35
	v_mad_u64_u32 v[26:27], s[38:39], v27, s48, v[2:3]
	v_mov_b32_e32 v35, v26
	global_load_dwordx2 v[26:27], v[34:35], off
